# all four big GEMM K-loops (in, out-proj, gate/up, down): 2-deep register prefetch with ds_write/global_load interleaved between MFMAs; MLA tile body regenerated (8-deep K-frag prefetch, exp/cvt of nex
# speedup vs baseline: 1.0321x; 1.0321x over previous
; #define G_STORE(BUF) do { char* l_ = lds + (BUF) * STAGE + wofs; \
;         *(uint4*)(l_) = ra0; *(uint4*)(l_ + 8192) = ra1; *(uint4*)(l_ + 16384) = ra2; if (MT == 4) *(uint4*)(l_ + 24576) = ra3; \
;         *(uint4*)(l_ + ABYTES) = rb0; *(uint4*)(l_ + ABYTES + 8192) = rb1; *(uint4*)(l_ + ABYTES + 16384) = rb2; *(uint4*)(l_ + ABYTES + 24576) = rb3; } while (0)
; template <int MT, bool PIN, class Epi>
; __device__ __forceinline__ void gemm_phase(const Params& P, const bf16_t* __restrict__ A, const bf16_t* __restrict__ Bt, int nM, int nN, int K, const Epi epi, char* lds) {
;     ...
;         const long L = (long)it * G + blockIdx.x; if (L >= nT) break;
;         int pm, pn; map_tile((int)L, nM, nN, pm, pn);
;         const char* Ab = (const char*)(A + (size_t)pm * BM * K);
;         const char* Bb = (const char*)(Bt + (size_t)pn * 256 * K);
;         const unsigned toff = (unsigned)(srow * K + sch * 8) * 2u, rs = (unsigned)K * 128u;
;         uint4 ra0, ra1, ra2, ra3, rb0, rb1, rb2, rb3;
;     ...
;         G_LOAD(0);
;         f32x16 acc[MT][2];
; #pragma unroll
;         for (int a = 0; a < MT; ++a)
; #pragma unroll
;             for (int b = 0; b < 2; ++b)
; #pragma unroll
;                 for (int e = 0; e < 16; ++e) acc[a][b][e] = 0.f;
;         bf16x8 fa[2][MT], fb[2][2];
;         __syncthreads();
;         G_STORE(0);
;         G_LOAD(1);
;         __syncthreads();
.LBB0_166:
	s_mul_i32 s0, s27, s33
	s_mul_hi_u32 s1, s27, s84
	s_add_i32 s1, s1, s0
	s_mul_i32 s0, s27, s84
	s_add_u32 s0, s0, s2
	s_addc_u32 s1, s1, 0
	v_cmp_gt_i64_e32 vcc, s[0:1], v[156:157]
	s_mov_b64 s[6:7], -1
	s_cbranch_vccnz .LBB0_165
	s_and_b32 s1, s0, 7
	s_mulk_i32 s1, 0xa5
	s_ashr_i32 s0, s0, 3
	s_add_i32 s1, s1, s0
	s_mul_hi_i32 s0, s1, 0x88888889
	s_add_i32 s0, s0, s1
	s_lshr_b32 s6, s0, 31
	s_ashr_i32 s0, s0, 6
	s_add_i32 s0, s0, s6
	s_lshl_b32 s6, s0, 3
	s_sub_i32 s7, 0x58, s6
	s_min_i32 s7, s7, 8
	s_abs_i32 s24, s7
	v_cvt_f32_u32_e32 v0, s24
	s_sub_i32 s29, 0, s24
	s_mulk_i32 s0, 0x78
	s_sub_i32 s1, s1, s0
	v_rcp_iflag_f32_e32 v0, v0
	s_abs_i32 s0, s1
	s_xor_b32 s28, s1, s7
	s_ashr_i32 s28, s28, 31
	v_mul_f32_e32 v0, 0x4f7ffffe, v0
	v_cvt_u32_f32_e32 v0, v0
	s_nop 0
	v_readfirstlane_b32 s30, v0
	s_mul_i32 s29, s29, s30
	s_mul_hi_u32 s29, s30, s29
	s_add_i32 s30, s30, s29
	s_mul_hi_u32 s29, s0, s30
	s_mul_i32 s30, s29, s24
	s_sub_i32 s0, s0, s30
	s_add_i32 s31, s29, 1
	s_sub_i32 s30, s0, s24
	s_cmp_ge_u32 s0, s24
	s_cselect_b32 s29, s31, s29
	s_cselect_b32 s0, s30, s0
	s_add_i32 s30, s29, 1
	s_cmp_ge_u32 s0, s24
	s_cselect_b32 s0, s30, s29
	s_xor_b32 s0, s0, s28
	s_sub_i32 s0, s0, s28
	s_mul_i32 s7, s0, s7
	s_sub_i32 s24, s1, s7
	s_add_i32 s24, s24, s6
	s_mul_i32 s6, s24, 0xc0000
	s_mul_hi_i32 s1, s24, 0xc0000
	s_add_u32 s6, s90, s6
	s_addc_u32 s7, s91, s1
	s_ashr_i32 s1, s0, 31
	s_lshl_b64 s[28:29], s[0:1], 20
	v_readlane_b32 s1, v252, 36
	v_lshl_add_u64 v[28:29], s[6:7], 0, v[130:131]
	v_lshl_add_u64 v[0:1], s[6:7], 0, v[134:135]
	s_add_u32 s76, s1, s28
	v_readlane_b32 s1, v252, 37
	global_load_dwordx4 v[38:41], v[28:29], off
	global_load_dwordx4 v[42:45], v[0:1], off
	v_lshl_add_u64 v[0:1], s[6:7], 0, v[136:137]
	s_addc_u32 s77, s1, s29
	v_lshl_add_u64 v[32:33], s[6:7], 0, v[140:141]
	v_lshl_add_u64 v[30:31], s[76:77], 0, v[130:131]
	s_waitcnt lgkmcnt(0)
	v_lshl_add_u64 v[2:3], s[76:77], 0, v[134:135]
	v_lshl_add_u64 v[4:5], s[76:77], 0, v[136:137]
	v_lshl_add_u64 v[6:7], s[76:77], 0, v[138:139]
	global_load_dwordx4 v[46:49], v[0:1], off
	global_load_dwordx4 v[50:53], v[30:31], off
	global_load_dwordx4 v[54:57], v[2:3], off
	global_load_dwordx4 v[58:61], v[4:5], off
	global_load_dwordx4 v[62:65], v[6:7], off
	v_lshl_add_u64 v[34:35], s[6:7], 0, v[142:143]
	v_lshl_add_u64 v[36:37], s[76:77], 0, v[140:141]
	v_lshl_add_u64 v[66:67], s[76:77], 0, v[142:143]
	v_lshl_add_u64 v[68:69], s[76:77], 0, v[144:145]
	s_barrier
	global_load_dwordx4 v[96:99], v[28:29], off offset:128
	global_load_dwordx4 v[100:103], v[32:33], off
	global_load_dwordx4 v[108:111], v[34:35], off
	global_load_dwordx4 v[104:107], v[30:31], off offset:128
	global_load_dwordx4 v[112:115], v[36:37], off
	global_load_dwordx4 v[116:119], v[66:67], off
	global_load_dwordx4 v[120:123], v[68:69], off
	global_load_dwordx4 v[212:215], v[28:29], off offset:256
	global_load_dwordx4 v[216:219], v[32:33], off offset:128
	global_load_dwordx4 v[220:223], v[34:35], off offset:128
	global_load_dwordx4 v[224:227], v[30:31], off offset:256
	global_load_dwordx4 v[228:231], v[36:37], off offset:128
	global_load_dwordx4 v[232:235], v[66:67], off offset:128
	global_load_dwordx4 v[236:239], v[68:69], off offset:128
	v_mov_b32_e32 v0, 0
	s_mov_b32 s28, 0
	s_movk_i32 s1, 0x180
	v_mov_b32_e32 v1, v0
	v_mov_b32_e32 v2, v0
	v_mov_b32_e32 v3, v0
	v_mov_b32_e32 v4, v0
	v_mov_b32_e32 v5, v0
	v_mov_b32_e32 v6, v0
	v_mov_b32_e32 v7, v0
	v_mov_b32_e32 v8, v0
	v_mov_b32_e32 v9, v0
	v_mov_b32_e32 v10, v0
	v_mov_b32_e32 v11, v0
	v_mov_b32_e32 v12, v0
	v_mov_b32_e32 v13, v0
	v_mov_b32_e32 v14, v0
	v_mov_b32_e32 v15, v0
	v_mov_b32_e32 v16, v0
	v_mov_b32_e32 v17, v0
	v_mov_b32_e32 v18, v0
	v_mov_b32_e32 v19, v0
	v_mov_b32_e32 v20, v0
	v_mov_b32_e32 v21, v0
	v_mov_b32_e32 v22, v0
	v_mov_b32_e32 v23, v0
	v_mov_b32_e32 v24, v0
	v_mov_b32_e32 v25, v0
	v_mov_b32_e32 v26, v0
	v_mov_b32_e32 v27, v0
	v_mov_b32_e32 v28, v0
	v_mov_b32_e32 v29, v0
	v_mov_b32_e32 v30, v0
	v_mov_b32_e32 v31, v0
	v_mov_b32_e32 v32, v0
	v_mov_b32_e32 v33, v0
	v_mov_b32_e32 v34, v0
	v_mov_b32_e32 v35, v0
	v_mov_b32_e32 v36, v0
	v_mov_b32_e32 v37, v0
	v_mov_b32_e32 v66, v0
	v_mov_b32_e32 v67, v0
	v_mov_b32_e32 v68, v0
	v_mov_b32_e32 v69, v0
	v_mov_b32_e32 v70, v0
	v_mov_b32_e32 v71, v0
	v_mov_b32_e32 v72, v0
	v_mov_b32_e32 v73, v0
	v_mov_b32_e32 v74, v0
	v_mov_b32_e32 v75, v0
	v_mov_b32_e32 v76, v0
	v_mov_b32_e32 v77, v0
	v_mov_b32_e32 v78, v0
	v_mov_b32_e32 v79, v0
	s_waitcnt vmcnt(20)
	ds_write_b128 v127, v[38:41]
	s_waitcnt vmcnt(19)
	ds_write_b128 v127, v[42:45] offset:8192
	s_waitcnt vmcnt(18)
	ds_write_b128 v127, v[46:49] offset:16384
	s_waitcnt vmcnt(17)
	ds_write_b128 v127, v[50:53] offset:24576
	s_waitcnt vmcnt(16)
	ds_write_b128 v127, v[54:57] offset:32768
	s_waitcnt vmcnt(15)
	ds_write_b128 v127, v[58:61] offset:40960
	s_waitcnt vmcnt(14)
	ds_write_b128 v127, v[62:65] offset:49152
	v_mov_b32_e32 v38, v0
	v_mov_b32_e32 v39, v0
	v_mov_b32_e32 v40, v0
	v_mov_b32_e32 v41, v0
	v_mov_b32_e32 v42, v0
	v_mov_b32_e32 v43, v0
	v_mov_b32_e32 v44, v0
	v_mov_b32_e32 v45, v0
	v_mov_b32_e32 v46, v0
	v_mov_b32_e32 v47, v0
	v_mov_b32_e32 v48, v0
	v_mov_b32_e32 v49, v0
	v_mov_b32_e32 v50, v0
	v_mov_b32_e32 v51, v0
	v_mov_b32_e32 v52, v0
	v_mov_b32_e32 v53, v0
	v_mov_b32_e32 v54, v0
	v_mov_b32_e32 v55, v0
	v_mov_b32_e32 v56, v0
	v_mov_b32_e32 v57, v0
	v_mov_b32_e32 v58, v0
	v_mov_b32_e32 v59, v0
	v_mov_b32_e32 v60, v0
	v_mov_b32_e32 v61, v0
	v_mov_b32_e32 v62, v0
	v_mov_b32_e32 v63, v0
	v_mov_b32_e32 v64, v0
	v_mov_b32_e32 v65, v0
	v_mov_b32_e32 v80, v0
	v_mov_b32_e32 v81, v0
	v_mov_b32_e32 v82, v0
	v_mov_b32_e32 v83, v0
	v_mov_b32_e32 v84, v0
	v_mov_b32_e32 v85, v0
	v_mov_b32_e32 v86, v0
	v_mov_b32_e32 v87, v0
	v_mov_b32_e32 v88, v0
	v_mov_b32_e32 v89, v0
	v_mov_b32_e32 v90, v0
	v_mov_b32_e32 v91, v0
	v_mov_b32_e32 v92, v0
	v_mov_b32_e32 v93, v0
	v_mov_b32_e32 v94, v0
	v_mov_b32_e32 v95, v0
	s_waitcnt lgkmcnt(0)
	s_barrier
.LBB0_168:
	v_add_u32_e32 v194, v158, v129
	ds_read_b128 v[178:181], v147
	ds_read_b128 v[182:185], v147 offset:4096
	ds_read_b128 v[186:189], v147 offset:8192
	ds_read_b128 v[190:193], v194 offset:24576
	ds_read_b128 v[194:197], v194 offset:28672
	s_add_i32 s29, s28, 2
	s_min_u32 s30, s1, 0xf80
	s_add_i32 s98, s1, 0x80
	s_min_u32 s98, s98, 0xf80
	s_addk_i32 s1, 0x100
	v_add_u32_e32 v240, s30, v130
	v_add_u32_e32 v241, 0x40000, v240
	v_add_u32_e32 v242, 0x80000, v240
	v_add_u32_e32 v243, 0xc0000, v240
	s_waitcnt lgkmcnt(1)
	v_mfma_f32_32x32x16_bf16 v[80:95], v[178:181], v[190:193], v[80:95]
	v_add_u32_e32 v206, v158, v162
	v_add_u32_e32 v132, v167, v129
	s_waitcnt lgkmcnt(0)
	v_mfma_f32_32x32x16_bf16 v[64:79], v[178:181], v[194:197], v[64:79]
	ds_read_b128 v[178:181], v161
	s_waitcnt vmcnt(13)
	ds_write_b128 v127, v[96:99] offset:57344
	global_load_dwordx4 v[96:99], v240, s[6:7]
	v_mfma_f32_32x32x16_bf16 v[48:63], v[182:185], v[190:193], v[48:63]
	v_mfma_f32_32x32x16_bf16 v[32:47], v[182:185], v[194:197], v[32:47]
	s_waitcnt vmcnt(13)
	ds_write_b128 v159, v[100:103] offset:8192
	global_load_dwordx4 v[100:103], v241, s[6:7]
	v_mfma_f32_32x32x16_bf16 v[0:15], v[186:189], v[194:197], v[0:15]
	v_add_u32_e32 v194, v158, v160
	v_mfma_f32_32x32x16_bf16 v[16:31], v[186:189], v[190:193], v[16:31]
	ds_read_b128 v[182:185], v194 offset:24576
	ds_read_b128 v[186:189], v161 offset:4096
	ds_read_b128 v[190:193], v165 offset:8192
	ds_read_b128 v[194:197], v194 offset:28672
	ds_read_b128 v[202:205], v206 offset:24576
	s_waitcnt vmcnt(13)
	ds_write_b128 v159, v[108:111] offset:16384
	global_load_dwordx4 v[108:111], v242, s[6:7]
	s_waitcnt lgkmcnt(5)
	v_mfma_f32_32x32x16_bf16 v[80:95], v[178:181], v[182:185], v[80:95]
	s_waitcnt lgkmcnt(2)
	v_mfma_f32_32x32x16_bf16 v[64:79], v[178:181], v[194:197], v[64:79]
	s_waitcnt vmcnt(13)
	ds_write_b128 v159, v[104:107] offset:24576
	global_load_dwordx4 v[104:107], v240, s[76:77]
	v_mfma_f32_32x32x16_bf16 v[48:63], v[186:189], v[182:185], v[48:63]
	v_mfma_f32_32x32x16_bf16 v[32:47], v[186:189], v[194:197], v[32:47]
	ds_read_b128 v[178:181], v161 offset:8192
	ds_read_b128 v[186:189], v163
	s_waitcnt vmcnt(13)
	ds_write_b128 v159, v[112:115] offset:32768
	global_load_dwordx4 v[112:115], v241, s[76:77]
	s_waitcnt lgkmcnt(2)
	v_mfma_f32_32x32x16_bf16 v[16:31], v[178:181], v[182:185], v[16:31]
	v_mfma_f32_32x32x16_bf16 v[0:15], v[178:181], v[194:197], v[0:15]
	ds_read_b128 v[178:181], v206 offset:28672
	v_add_u32_e32 v206, v158, v164
	ds_read_b128 v[182:185], v206 offset:24576
	s_waitcnt vmcnt(13)
	ds_write_b128 v159, v[116:119] offset:40960
	global_load_dwordx4 v[116:119], v242, s[76:77]
	s_waitcnt lgkmcnt(4)
	v_mfma_f32_32x32x16_bf16 v[80:95], v[186:189], v[202:205], v[80:95]
	s_waitcnt lgkmcnt(2)
	v_mfma_f32_32x32x16_bf16 v[64:79], v[186:189], v[178:181], v[64:79]
	ds_read_b128 v[186:189], v163 offset:4096
	ds_read_b128 v[194:197], v163 offset:8192
	s_waitcnt vmcnt(13)
	ds_write_b128 v159, v[120:123] offset:49152
	global_load_dwordx4 v[120:123], v243, s[76:77]
	s_waitcnt lgkmcnt(2)
	v_mfma_f32_32x32x16_bf16 v[48:63], v[186:189], v[202:205], v[48:63]
	v_mfma_f32_32x32x16_bf16 v[32:47], v[186:189], v[178:181], v[32:47]
	s_waitcnt lgkmcnt(1)
	v_mfma_f32_32x32x16_bf16 v[16:31], v[194:197], v[202:205], v[16:31]
	v_mfma_f32_32x32x16_bf16 v[0:15], v[194:197], v[178:181], v[0:15]
	ds_read_b128 v[178:181], v165
	ds_read_b128 v[186:189], v165 offset:4096
	ds_read_b128 v[194:197], v206 offset:28672
	s_waitcnt lgkmcnt(0)
	s_barrier
	v_mfma_f32_32x32x16_bf16 v[80:95], v[178:181], v[182:185], v[80:95]
	v_mfma_f32_32x32x16_bf16 v[64:79], v[178:181], v[194:197], v[64:79]
	v_mfma_f32_32x32x16_bf16 v[48:63], v[186:189], v[182:185], v[48:63]
	v_mfma_f32_32x32x16_bf16 v[32:47], v[186:189], v[194:197], v[32:47]
	ds_read_b128 v[178:181], v147 offset:57344
	ds_read_b128 v[186:189], v147 offset:61440
	ds_read_b128 v[202:205], v166 offset:8192
	ds_read_b128 v[206:209], v173
	v_mfma_f32_32x32x16_bf16 v[16:31], v[190:193], v[182:185], v[16:31]
	ds_read_b128 v[182:185], v132 offset:4096
	v_add_u32_e32 v240, s98, v130
	v_add_u32_e32 v241, 0x40000, v240
	v_add_u32_e32 v242, 0x80000, v240
	v_add_u32_e32 v243, 0xc0000, v240
	s_waitcnt vmcnt(13)
	ds_write_b128 v127, v[212:215]
	global_load_dwordx4 v[212:215], v240, s[6:7]
	v_mfma_f32_32x32x16_bf16 v[0:15], v[190:193], v[194:197], v[0:15]
	s_waitcnt lgkmcnt(2)
	v_mfma_f32_32x32x16_bf16 v[80:95], v[178:181], v[206:209], v[80:95]
	v_add_u32_e32 v194, v167, v160
	s_mov_b32 s28, s29
	s_waitcnt lgkmcnt(1)
	v_mfma_f32_32x32x16_bf16 v[64:79], v[178:181], v[182:185], v[64:79]
	s_waitcnt vmcnt(13)
	ds_write_b128 v127, v[216:219] offset:8192
	global_load_dwordx4 v[216:219], v241, s[6:7]
	v_mfma_f32_32x32x16_bf16 v[48:63], v[186:189], v[206:209], v[48:63]
	v_mfma_f32_32x32x16_bf16 v[32:47], v[186:189], v[182:185], v[32:47]
	s_waitcnt vmcnt(13)
	ds_write_b128 v127, v[220:223] offset:16384
	global_load_dwordx4 v[220:223], v242, s[6:7]
	v_mfma_f32_32x32x16_bf16 v[16:31], v[202:205], v[206:209], v[16:31]
	v_mfma_f32_32x32x16_bf16 v[0:15], v[202:205], v[182:185], v[0:15]
	ds_read_b128 v[178:181], v161 offset:57344
	ds_read_b128 v[182:185], v174
	ds_read_b128 v[186:189], v161 offset:61440
	ds_read_b128 v[190:193], v170 offset:8192
	ds_read_b128 v[194:197], v194 offset:4096
	ds_read_b128 v[202:205], v175
	s_waitcnt vmcnt(13)
	ds_write_b128 v127, v[224:227] offset:24576
	global_load_dwordx4 v[224:227], v240, s[76:77]
	s_waitcnt lgkmcnt(5)
	v_mfma_f32_32x32x16_bf16 v[80:95], v[178:181], v[182:185], v[80:95]
	s_waitcnt lgkmcnt(2)
	v_mfma_f32_32x32x16_bf16 v[64:79], v[178:181], v[194:197], v[64:79]
	s_waitcnt vmcnt(13)
;     template <int MT> __device__ __forceinline__ void run(const Params& P, f32x16 (&acc)[MT][2], int rbase, int pn, int wc, int lane) const {
;     ...
;             if (wc == 0 && n < 16) { float* WI = (float*)(ws + OFF_WI);
; #pragma unroll
;                 for (int mt = 0; mt < MT; ++mt)
; #pragma unroll
;                     for (int rg = 0; rg < 16; ++rg) { const int r = ROWOF(rb, mt, rg); WI[(size_t)r * 16 + n] = acc[mt][0][rg] * 0.03125f; } }
	ds_write_b128 v127, v[228:231] offset:32768
	global_load_dwordx4 v[228:231], v241, s[76:77]
	v_mfma_f32_32x32x16_bf16 v[48:63], v[186:189], v[182:185], v[48:63]
	v_mfma_f32_32x32x16_bf16 v[32:47], v[186:189], v[194:197], v[32:47]
	ds_read_b128 v[178:181], v168 offset:8192
	ds_read_b128 v[186:189], v169 offset:8192
	s_waitcnt vmcnt(13)
	ds_write_b128 v127, v[232:235] offset:40960
	global_load_dwordx4 v[232:235], v242, s[76:77]
	s_waitcnt lgkmcnt(2)
	v_mfma_f32_32x32x16_bf16 v[16:31], v[178:181], v[182:185], v[16:31]
	v_mfma_f32_32x32x16_bf16 v[0:15], v[178:181], v[194:197], v[0:15]
	ds_read_b128 v[178:181], v163 offset:57344
	ds_read_b128 v[182:185], v163 offset:61440
	v_add_u32_e32 v194, v167, v162
	ds_read_b128 v[194:197], v194 offset:4096
	ds_read_b128 v[206:209], v176
	s_waitcnt vmcnt(13)
	ds_write_b128 v127, v[236:239] offset:49152
	global_load_dwordx4 v[236:239], v243, s[76:77]
	s_waitcnt lgkmcnt(4)
	v_mfma_f32_32x32x16_bf16 v[80:95], v[178:181], v[202:205], v[80:95]
	s_waitcnt lgkmcnt(2)
	v_mfma_f32_32x32x16_bf16 v[64:79], v[178:181], v[194:197], v[64:79]
	v_mfma_f32_32x32x16_bf16 v[48:63], v[182:185], v[202:205], v[48:63]
	v_mfma_f32_32x32x16_bf16 v[32:47], v[182:185], v[194:197], v[32:47]
	ds_read_b128 v[178:181], v165 offset:57344
	ds_read_b128 v[182:185], v165 offset:61440
	v_mfma_f32_32x32x16_bf16 v[16:31], v[186:189], v[202:205], v[16:31]
	v_mfma_f32_32x32x16_bf16 v[0:15], v[186:189], v[194:197], v[0:15]
	v_add_u32_e32 v186, v167, v164
	ds_read_b128 v[186:189], v186 offset:4096
	s_waitcnt lgkmcnt(0)
	s_barrier
	v_mfma_f32_32x32x16_bf16 v[80:95], v[178:181], v[206:209], v[80:95]
	v_mfma_f32_32x32x16_bf16 v[64:79], v[178:181], v[186:189], v[64:79]
	v_mfma_f32_32x32x16_bf16 v[48:63], v[182:185], v[206:209], v[48:63]
	v_mfma_f32_32x32x16_bf16 v[32:47], v[182:185], v[186:189], v[32:47]
	v_mfma_f32_32x32x16_bf16 v[16:31], v[190:193], v[206:209], v[16:31]
	v_mfma_f32_32x32x16_bf16 v[0:15], v[190:193], v[186:189], v[0:15]
	s_cmp_lt_u32 s28, 32
	s_cbranch_scc1 .LBB0_168
	s_mul_i32 s39, s24, 0xc0
	v_readlane_b32 s1, v252, 38
	s_lshl_b32 s6, s0, 1
	v_readlane_b32 s0, v252, 40
	s_add_i32 s39, s39, s1
	s_or_b32 s38, s6, s0
	s_waitcnt vmcnt(0)
	v_or_b32_e32 v96, s39, v171
	s_cmp_gt_i32 s38, 3
	s_mov_b64 s[0:1], -1
	s_cbranch_scc0 .LBB0_887
	s_cmp_gt_u32 s6, 7
	s_cbranch_scc0 .LBB0_692
	s_cmp_lg_u32 s38, 8
	s_cbranch_scc0 .LBB0_474
	s_cmp_gt_u32 s38, 18
	s_cbranch_scc0 .LBB0_280
	s_cmp_gt_u32 s38, 20
	s_cbranch_scc0 .LBB0_181
	s_cmp_gt_u32 s38, 28
	s_cbranch_scc0 .LBB0_178
	s_mov_b64 s[0:1], exec
	v_readlane_b32 s6, v252, 43
	v_readlane_b32 s7, v252, 44
	s_and_b64 s[6:7], s[0:1], s[6:7]
	s_mov_b64 exec, s[6:7]
	s_cbranch_execz .LBB0_177
	v_ashrrev_i32_e32 v97, 31, v96
	v_lshlrev_b64 v[98:99], 6, v[96:97]
	s_waitcnt vmcnt(4)
	v_mul_f32_e32 v100, 0x3d000000, v80
	v_lshl_add_u64 v[98:99], v[152:153], 0, v[98:99]
	global_store_dword v[98:99], v100, off
	v_or_b32_e32 v100, 1, v96
	v_ashrrev_i32_e32 v101, 31, v100
	v_lshlrev_b64 v[100:101], 6, v[100:101]
	v_mul_f32_e32 v97, 0x3d000000, v81
	v_lshl_add_u64 v[100:101], v[152:153], 0, v[100:101]
	global_store_dword v[100:101], v97, off
	v_or_b32_e32 v100, 2, v96
	v_ashrrev_i32_e32 v101, 31, v100
	v_lshlrev_b64 v[100:101], 6, v[100:101]
	v_mul_f32_e32 v97, 0x3d000000, v82
	v_lshl_add_u64 v[100:101], v[152:153], 0, v[100:101]
	global_store_dword v[100:101], v97, off
	v_or_b32_e32 v100, 3, v96
	v_ashrrev_i32_e32 v101, 31, v100
	v_lshlrev_b64 v[100:101], 6, v[100:101]
	v_mul_f32_e32 v97, 0x3d000000, v83
	v_lshl_add_u64 v[100:101], v[152:153], 0, v[100:101]
	global_store_dword v[100:101], v97, off
	v_or_b32_e32 v100, 8, v96
	v_ashrrev_i32_e32 v101, 31, v100
	v_lshlrev_b64 v[100:101], 6, v[100:101]
	v_mul_f32_e32 v97, 0x3d000000, v84
	v_lshl_add_u64 v[100:101], v[152:153], 0, v[100:101]
	global_store_dword v[100:101], v97, off
	v_or_b32_e32 v100, 9, v96
	v_ashrrev_i32_e32 v101, 31, v100
	v_lshlrev_b64 v[100:101], 6, v[100:101]
	v_mul_f32_e32 v97, 0x3d000000, v85
	v_lshl_add_u64 v[100:101], v[152:153], 0, v[100:101]
	global_store_dword v[100:101], v97, off
	v_or_b32_e32 v100, 10, v96
	v_ashrrev_i32_e32 v101, 31, v100
	v_lshlrev_b64 v[100:101], 6, v[100:101]
	v_mul_f32_e32 v97, 0x3d000000, v86
	v_lshl_add_u64 v[100:101], v[152:153], 0, v[100:101]
	global_store_dword v[100:101], v97, off
	v_or_b32_e32 v100, 11, v96
	v_ashrrev_i32_e32 v101, 31, v100
	v_lshlrev_b64 v[100:101], 6, v[100:101]
	v_mul_f32_e32 v97, 0x3d000000, v87
	v_lshl_add_u64 v[100:101], v[152:153], 0, v[100:101]
	global_store_dword v[100:101], v97, off
	v_or_b32_e32 v100, 16, v96
	v_ashrrev_i32_e32 v101, 31, v100
	v_lshlrev_b64 v[100:101], 6, v[100:101]
	v_mul_f32_e32 v97, 0x3d000000, v88
	v_lshl_add_u64 v[100:101], v[152:153], 0, v[100:101]
	global_store_dword v[100:101], v97, off
	v_or_b32_e32 v100, 17, v96
	v_ashrrev_i32_e32 v101, 31, v100
	v_lshlrev_b64 v[100:101], 6, v[100:101]
	v_mul_f32_e32 v97, 0x3d000000, v89
	v_lshl_add_u64 v[100:101], v[152:153], 0, v[100:101]
	global_store_dword v[100:101], v97, off
	v_or_b32_e32 v100, 18, v96
	v_ashrrev_i32_e32 v101, 31, v100
	v_lshlrev_b64 v[100:101], 6, v[100:101]
	v_mul_f32_e32 v97, 0x3d000000, v90
	v_lshl_add_u64 v[100:101], v[152:153], 0, v[100:101]
	global_store_dword v[100:101], v97, off
	v_or_b32_e32 v100, 19, v96
	v_ashrrev_i32_e32 v101, 31, v100
	v_lshlrev_b64 v[100:101], 6, v[100:101]
	v_mul_f32_e32 v97, 0x3d000000, v91
	v_lshl_add_u64 v[100:101], v[152:153], 0, v[100:101]
	global_store_dword v[100:101], v97, off
	v_or_b32_e32 v100, 24, v96
	v_ashrrev_i32_e32 v101, 31, v100
	v_lshlrev_b64 v[100:101], 6, v[100:101]
	v_mul_f32_e32 v97, 0x3d000000, v92
	v_lshl_add_u64 v[100:101], v[152:153], 0, v[100:101]
;     template <int MT> __device__ __forceinline__ void run(const Params& P, f32x16 (&acc)[MT][2], int rbase, int pn, int wc, int lane) const {
;     ...
;             if (wc == 0 && n < 16) { float* WI = (float*)(ws + OFF_WI);
; #pragma unroll
;                 for (int mt = 0; mt < MT; ++mt)
; #pragma unroll
;                     for (int rg = 0; rg < 16; ++rg) { const int r = ROWOF(rb, mt, rg); WI[(size_t)r * 16 + n] = acc[mt][0][rg] * 0.03125f; } }
	global_store_dword v[100:101], v97, off
	v_or_b32_e32 v100, 25, v96
	v_ashrrev_i32_e32 v101, 31, v100
	v_lshlrev_b64 v[100:101], 6, v[100:101]
	v_mul_f32_e32 v97, 0x3d000000, v93
	v_lshl_add_u64 v[100:101], v[152:153], 0, v[100:101]
	global_store_dword v[100:101], v97, off
	v_or_b32_e32 v100, 26, v96
	v_ashrrev_i32_e32 v101, 31, v100
	v_lshlrev_b64 v[100:101], 6, v[100:101]
	v_mul_f32_e32 v97, 0x3d000000, v94
	v_lshl_add_u64 v[100:101], v[152:153], 0, v[100:101]
	global_store_dword v[100:101], v97, off
	v_or_b32_e32 v100, 27, v96
	v_ashrrev_i32_e32 v101, 31, v100
	v_lshlrev_b64 v[100:101], 6, v[100:101]
	v_mul_f32_e32 v97, 0x3d000000, v95
	v_lshl_add_u64 v[100:101], v[152:153], 0, v[100:101]
	global_store_dword v[100:101], v97, off
	v_add_u32_e32 v100, 33, v96
	v_ashrrev_i32_e32 v101, 31, v100
	v_mul_f32_e32 v97, 0x3d000000, v48
	v_lshlrev_b64 v[100:101], 6, v[100:101]
	global_store_dword v[98:99], v97, off offset:2048
	v_mul_f32_e32 v97, 0x3d000000, v49
	v_lshl_add_u64 v[100:101], v[152:153], 0, v[100:101]
	global_store_dword v[100:101], v97, off
	v_add_u32_e32 v100, 34, v96
	v_ashrrev_i32_e32 v101, 31, v100
	v_lshlrev_b64 v[100:101], 6, v[100:101]
	v_mul_f32_e32 v97, 0x3d000000, v50
	v_lshl_add_u64 v[100:101], v[152:153], 0, v[100:101]
	global_store_dword v[100:101], v97, off
	v_add_u32_e32 v100, 35, v96
	v_ashrrev_i32_e32 v101, 31, v100
	v_lshlrev_b64 v[100:101], 6, v[100:101]
	v_mul_f32_e32 v97, 0x3d000000, v51
	v_lshl_add_u64 v[100:101], v[152:153], 0, v[100:101]
	global_store_dword v[100:101], v97, off
	v_add_u32_e32 v100, 40, v96
	v_ashrrev_i32_e32 v101, 31, v100
	v_lshlrev_b64 v[100:101], 6, v[100:101]
	v_mul_f32_e32 v97, 0x3d000000, v52
	v_lshl_add_u64 v[100:101], v[152:153], 0, v[100:101]
	global_store_dword v[100:101], v97, off
	v_add_u32_e32 v100, 41, v96
	v_ashrrev_i32_e32 v101, 31, v100
	v_lshlrev_b64 v[100:101], 6, v[100:101]
	v_mul_f32_e32 v97, 0x3d000000, v53
	v_lshl_add_u64 v[100:101], v[152:153], 0, v[100:101]
	global_store_dword v[100:101], v97, off
	v_add_u32_e32 v100, 42, v96
	v_ashrrev_i32_e32 v101, 31, v100
	v_lshlrev_b64 v[100:101], 6, v[100:101]
	v_mul_f32_e32 v97, 0x3d000000, v54
	v_lshl_add_u64 v[100:101], v[152:153], 0, v[100:101]
	global_store_dword v[100:101], v97, off
	v_add_u32_e32 v100, 43, v96
	v_ashrrev_i32_e32 v101, 31, v100
	v_lshlrev_b64 v[100:101], 6, v[100:101]
	v_mul_f32_e32 v97, 0x3d000000, v55
	v_lshl_add_u64 v[100:101], v[152:153], 0, v[100:101]
	global_store_dword v[100:101], v97, off
	v_add_u32_e32 v100, 48, v96
	v_ashrrev_i32_e32 v101, 31, v100
	v_lshlrev_b64 v[100:101], 6, v[100:101]
	v_mul_f32_e32 v97, 0x3d000000, v56
	v_lshl_add_u64 v[100:101], v[152:153], 0, v[100:101]
	global_store_dword v[100:101], v97, off
	v_add_u32_e32 v100, 49, v96
	v_ashrrev_i32_e32 v101, 31, v100
	v_lshlrev_b64 v[100:101], 6, v[100:101]
	v_mul_f32_e32 v97, 0x3d000000, v57
	v_lshl_add_u64 v[100:101], v[152:153], 0, v[100:101]
	global_store_dword v[100:101], v97, off
	v_add_u32_e32 v100, 50, v96
	v_ashrrev_i32_e32 v101, 31, v100
	v_lshlrev_b64 v[100:101], 6, v[100:101]
	v_mul_f32_e32 v97, 0x3d000000, v58
	v_lshl_add_u64 v[100:101], v[152:153], 0, v[100:101]
	global_store_dword v[100:101], v97, off
	v_add_u32_e32 v100, 51, v96
	v_ashrrev_i32_e32 v101, 31, v100
	v_lshlrev_b64 v[100:101], 6, v[100:101]
	v_mul_f32_e32 v97, 0x3d000000, v59
	v_lshl_add_u64 v[100:101], v[152:153], 0, v[100:101]
	global_store_dword v[100:101], v97, off
	v_add_u32_e32 v100, 56, v96
	v_ashrrev_i32_e32 v101, 31, v100
	v_lshlrev_b64 v[100:101], 6, v[100:101]
	v_mul_f32_e32 v97, 0x3d000000, v60
	v_lshl_add_u64 v[100:101], v[152:153], 0, v[100:101]
	global_store_dword v[100:101], v97, off
	v_add_u32_e32 v100, 57, v96
	v_ashrrev_i32_e32 v101, 31, v100
	v_lshlrev_b64 v[100:101], 6, v[100:101]
	v_mul_f32_e32 v97, 0x3d000000, v61
	v_lshl_add_u64 v[100:101], v[152:153], 0, v[100:101]
	global_store_dword v[100:101], v97, off
	v_add_u32_e32 v100, 58, v96
	v_ashrrev_i32_e32 v101, 31, v100
;     template <int MT> __device__ __forceinline__ void run(const Params& P, f32x16 (&acc)[MT][2], int rbase, int pn, int wc, int lane) const {
;     ...
;             if (wc == 0 && n < 16) { float* WI = (float*)(ws + OFF_WI);
; #pragma unroll
;                 for (int mt = 0; mt < MT; ++mt)
; #pragma unroll
;                     for (int rg = 0; rg < 16; ++rg) { const int r = ROWOF(rb, mt, rg); WI[(size_t)r * 16 + n] = acc[mt][0][rg] * 0.03125f; } }
	v_lshlrev_b64 v[100:101], 6, v[100:101]
	v_mul_f32_e32 v97, 0x3d000000, v62
	v_lshl_add_u64 v[100:101], v[152:153], 0, v[100:101]
	global_store_dword v[100:101], v97, off
	v_add_u32_e32 v100, 59, v96
	v_ashrrev_i32_e32 v101, 31, v100
	v_lshlrev_b64 v[100:101], 6, v[100:101]
	s_movk_i32 s6, 0x1000
	v_mul_f32_e32 v97, 0x3d000000, v63
	v_lshl_add_u64 v[100:101], v[152:153], 0, v[100:101]
	v_add_co_u32_e32 v98, vcc, s6, v98
	global_store_dword v[100:101], v97, off
	v_mul_f32_e32 v97, 0x3d000000, v16
	v_addc_co_u32_e32 v99, vcc, 0, v99, vcc
	global_store_dword v[98:99], v97, off
	v_add_u32_e32 v98, 0x41, v96
	v_ashrrev_i32_e32 v99, 31, v98
	v_lshlrev_b64 v[98:99], 6, v[98:99]
	v_mul_f32_e32 v97, 0x3d000000, v17
	v_lshl_add_u64 v[98:99], v[152:153], 0, v[98:99]
	global_store_dword v[98:99], v97, off
	v_add_u32_e32 v98, 0x42, v96
	v_ashrrev_i32_e32 v99, 31, v98
	v_lshlrev_b64 v[98:99], 6, v[98:99]
	v_mul_f32_e32 v97, 0x3d000000, v18
	v_lshl_add_u64 v[98:99], v[152:153], 0, v[98:99]
	global_store_dword v[98:99], v97, off
	v_add_u32_e32 v98, 0x43, v96
	v_ashrrev_i32_e32 v99, 31, v98
	v_lshlrev_b64 v[98:99], 6, v[98:99]
	v_mul_f32_e32 v97, 0x3d000000, v19
	v_lshl_add_u64 v[98:99], v[152:153], 0, v[98:99]
	global_store_dword v[98:99], v97, off
	v_add_u32_e32 v98, 0x48, v96
	v_ashrrev_i32_e32 v99, 31, v98
	v_lshlrev_b64 v[98:99], 6, v[98:99]
	v_mul_f32_e32 v97, 0x3d000000, v20
	v_lshl_add_u64 v[98:99], v[152:153], 0, v[98:99]
	global_store_dword v[98:99], v97, off
	v_add_u32_e32 v98, 0x49, v96
	v_ashrrev_i32_e32 v99, 31, v98
	v_lshlrev_b64 v[98:99], 6, v[98:99]
	v_mul_f32_e32 v97, 0x3d000000, v21
	v_lshl_add_u64 v[98:99], v[152:153], 0, v[98:99]
	global_store_dword v[98:99], v97, off
	v_add_u32_e32 v98, 0x4a, v96
	v_ashrrev_i32_e32 v99, 31, v98
	v_lshlrev_b64 v[98:99], 6, v[98:99]
	v_mul_f32_e32 v97, 0x3d000000, v22
	v_lshl_add_u64 v[98:99], v[152:153], 0, v[98:99]
	global_store_dword v[98:99], v97, off
	v_add_u32_e32 v98, 0x4b, v96
	v_ashrrev_i32_e32 v99, 31, v98
	v_lshlrev_b64 v[98:99], 6, v[98:99]
	v_mul_f32_e32 v97, 0x3d000000, v23
	v_lshl_add_u64 v[98:99], v[152:153], 0, v[98:99]
	global_store_dword v[98:99], v97, off
	v_add_u32_e32 v98, 0x50, v96
	v_ashrrev_i32_e32 v99, 31, v98
	v_lshlrev_b64 v[98:99], 6, v[98:99]
	v_mul_f32_e32 v97, 0x3d000000, v24
	v_lshl_add_u64 v[98:99], v[152:153], 0, v[98:99]
	global_store_dword v[98:99], v97, off
	v_add_u32_e32 v98, 0x51, v96
	v_ashrrev_i32_e32 v99, 31, v98
	v_lshlrev_b64 v[98:99], 6, v[98:99]
	v_mul_f32_e32 v97, 0x3d000000, v25
	v_lshl_add_u64 v[98:99], v[152:153], 0, v[98:99]
	global_store_dword v[98:99], v97, off
	v_add_u32_e32 v98, 0x52, v96
	v_ashrrev_i32_e32 v99, 31, v98
	v_lshlrev_b64 v[98:99], 6, v[98:99]
	v_mul_f32_e32 v97, 0x3d000000, v26
	v_lshl_add_u64 v[98:99], v[152:153], 0, v[98:99]
	global_store_dword v[98:99], v97, off
	v_add_u32_e32 v98, 0x53, v96
	v_ashrrev_i32_e32 v99, 31, v98
	v_lshlrev_b64 v[98:99], 6, v[98:99]
	v_mul_f32_e32 v97, 0x3d000000, v27
	v_lshl_add_u64 v[98:99], v[152:153], 0, v[98:99]
	global_store_dword v[98:99], v97, off
	v_add_u32_e32 v98, 0x58, v96
	v_ashrrev_i32_e32 v99, 31, v98
	v_lshlrev_b64 v[98:99], 6, v[98:99]
	v_mul_f32_e32 v97, 0x3d000000, v28
	v_lshl_add_u64 v[98:99], v[152:153], 0, v[98:99]
	global_store_dword v[98:99], v97, off
	v_add_u32_e32 v98, 0x59, v96
	v_ashrrev_i32_e32 v99, 31, v98
	v_lshlrev_b64 v[98:99], 6, v[98:99]
	v_mul_f32_e32 v97, 0x3d000000, v29
	v_lshl_add_u64 v[98:99], v[152:153], 0, v[98:99]
	global_store_dword v[98:99], v97, off
	v_add_u32_e32 v98, 0x5a, v96
	v_ashrrev_i32_e32 v99, 31, v98
	v_lshlrev_b64 v[98:99], 6, v[98:99]
	v_mul_f32_e32 v97, 0x3d000000, v30
	v_lshl_add_u64 v[98:99], v[152:153], 0, v[98:99]
	global_store_dword v[98:99], v97, off
	v_add_u32_e32 v98, 0x5b, v96
	v_ashrrev_i32_e32 v99, 31, v98
	v_lshlrev_b64 v[98:99], 6, v[98:99]
	v_mul_f32_e32 v97, 0x3d000000, v31
	v_lshl_add_u64 v[98:99], v[152:153], 0, v[98:99]
	global_store_dword v[98:99], v97, off

.LBB0_1558:
	s_add_i32 s50, s46, -1
	v_min_u32_e32 v0, s50, v205
	v_mad_u64_u32 v[2:3], s[50:51], v0, s30, v[208:209]
	v_lshlrev_b32_e32 v0, 6, v0
	v_lshl_add_u64 v[4:5], v[0:1], 1, v[206:207]
	v_add_u32_e32 v0, 0xa800, v222
	s_add_i32 s47, s46, -4
	s_waitcnt vmcnt(7)
	ds_write_b128 v216, v[164:167] offset:43008
	s_waitcnt vmcnt(8)
	ds_write_b128 v217, v[160:163] offset:43008
	s_waitcnt vmcnt(7)
	ds_write_b128 v218, v[168:171] offset:43008
	s_waitcnt vmcnt(3)
	ds_write2_b64 v0, v[180:181], v[182:183] offset1:1
	v_add_u32_e32 v0, 0xca00, v222
	s_waitcnt vmcnt(1)
	ds_write2_b64 v0, v[188:189], v[190:191] offset1:1
	v_add_co_u32_e32 v6, vcc, 0x2000, v2
	s_nop 1
	v_addc_co_u32_e32 v7, vcc, 0, v3, vcc
	v_add_co_u32_e32 v8, vcc, 0x4000, v2
	s_nop 1
	v_addc_co_u32_e32 v9, vcc, 0, v3, vcc
	global_load_dwordx4 v[160:163], v[6:7], off
	global_load_dwordx4 v[168:171], v[8:9], off
	global_load_dwordx4 v[164:167], v[2:3], off
	global_load_dwordx4 v[180:183], v[4:5], off
	v_add_co_u32_e32 v2, vcc, 0x310000, v4
	s_nop 1
	v_addc_co_u32_e32 v3, vcc, 0, v5, vcc
	global_load_dwordx4 v[188:191], v[2:3], off
	s_cmp_ge_i32 s47, s43
	s_cbranch_scc1 .LBB0_1562
	ds_read_b128 v[4:7], v225
	ds_read_b128 v[8:11], v225 offset:12800
	ds_read_b128 v[12:15], v225 offset:32
	ds_read_b128 v[228:231], v225 offset:12832
	ds_read_b128 v[232:235], v225 offset:64
	ds_read_b128 v[236:239], v225 offset:12864
	ds_read_b128 v[240:243], v225 offset:96
	s_waitcnt lgkmcnt(6)
	v_mfma_f32_32x32x16_bf16 v[96:111], v[4:7], v[156:159], 0
	ds_read_b128 v[244:247], v225 offset:12896
	s_waitcnt lgkmcnt(6)
	v_mfma_f32_32x32x16_bf16 v[80:95], v[8:11], v[156:159], 0
	ds_read_b128 v[4:7], v225 offset:128
	s_waitcnt lgkmcnt(6)
	v_mfma_f32_32x32x16_bf16 v[96:111], v[12:15], v[152:155], v[96:111]
	ds_read_b128 v[8:11], v225 offset:12928
	s_waitcnt lgkmcnt(6)
	v_mfma_f32_32x32x16_bf16 v[80:95], v[228:231], v[152:155], v[80:95]
	ds_read_b128 v[12:15], v225 offset:160
	s_waitcnt lgkmcnt(6)
	v_mfma_f32_32x32x16_bf16 v[96:111], v[232:235], v[148:151], v[96:111]
	ds_read_b128 v[228:231], v225 offset:12960
	s_waitcnt lgkmcnt(6)
	v_mfma_f32_32x32x16_bf16 v[80:95], v[236:239], v[148:151], v[80:95]
	ds_read_b128 v[232:235], v225 offset:192
	s_waitcnt lgkmcnt(6)
	v_mfma_f32_32x32x16_bf16 v[96:111], v[240:243], v[144:147], v[96:111]
	ds_read_b128 v[236:239], v225 offset:12992
	s_waitcnt lgkmcnt(6)
	v_mfma_f32_32x32x16_bf16 v[80:95], v[244:247], v[144:147], v[80:95]
	ds_read_b128 v[240:243], v225 offset:224
	s_waitcnt lgkmcnt(6)
	v_mfma_f32_32x32x16_bf16 v[96:111], v[4:7], v[140:143], v[96:111]
	ds_read_b128 v[244:247], v225 offset:13024
	s_waitcnt lgkmcnt(6)
	v_mfma_f32_32x32x16_bf16 v[80:95], v[8:11], v[140:143], v[80:95]
	ds_read_b128 v[4:7], v225 offset:256
	s_waitcnt lgkmcnt(6)
	v_mfma_f32_32x32x16_bf16 v[96:111], v[12:15], v[136:139], v[96:111]
	ds_read_b128 v[8:11], v225 offset:13056
	s_waitcnt lgkmcnt(6)
	v_mfma_f32_32x32x16_bf16 v[80:95], v[228:231], v[136:139], v[80:95]
	ds_read_b128 v[12:15], v225 offset:288
	s_waitcnt lgkmcnt(6)
	v_mfma_f32_32x32x16_bf16 v[96:111], v[232:235], v[132:135], v[96:111]
	ds_read_b128 v[228:231], v225 offset:13088
	s_waitcnt lgkmcnt(6)
	v_mfma_f32_32x32x16_bf16 v[80:95], v[236:239], v[132:135], v[80:95]
	ds_read_b128 v[232:235], v225 offset:320
	s_waitcnt lgkmcnt(6)
	v_mfma_f32_32x32x16_bf16 v[96:111], v[240:243], v[128:131], v[96:111]
	ds_read_b128 v[236:239], v225 offset:13120
	s_waitcnt lgkmcnt(6)
	v_mfma_f32_32x32x16_bf16 v[80:95], v[244:247], v[128:131], v[80:95]
	ds_read_b128 v[240:243], v225 offset:352
	s_waitcnt lgkmcnt(6)
	v_mfma_f32_32x32x16_bf16 v[96:111], v[4:7], v[124:127], v[96:111]
	ds_read_b128 v[244:247], v225 offset:13152
	s_waitcnt lgkmcnt(6)
	v_mfma_f32_32x32x16_bf16 v[80:95], v[8:11], v[124:127], v[80:95]
	s_waitcnt lgkmcnt(5)
	v_mfma_f32_32x32x16_bf16 v[96:111], v[12:15], v[120:123], v[96:111]
	s_waitcnt lgkmcnt(4)
	v_mfma_f32_32x32x16_bf16 v[80:95], v[228:231], v[120:123], v[80:95]
	s_waitcnt lgkmcnt(3)
	v_mfma_f32_32x32x16_bf16 v[96:111], v[232:235], v[116:119], v[96:111]
	s_waitcnt lgkmcnt(2)
	v_mfma_f32_32x32x16_bf16 v[80:95], v[236:239], v[116:119], v[80:95]
	s_waitcnt lgkmcnt(1)
	v_mfma_f32_32x32x16_bf16 v[96:111], v[240:243], v[112:115], v[96:111]
	s_waitcnt lgkmcnt(0)
	v_mfma_f32_32x32x16_bf16 v[80:95], v[244:247], v[112:115], v[80:95]
	v_and_b32_e32 v248, 64, v210
	v_xor_b32_e32 v249, 32, v210
	v_add_u32_e32 v248, 64, v248
	v_cmp_lt_i32_e32 vcc, v249, v248
	ds_read_b64 v[228:229], v223 offset:25600
	ds_read_b64 v[230:231], v223 offset:25616
	ds_read_b64 v[232:233], v223 offset:29952
	ds_read_b64 v[234:235], v223 offset:29968
	ds_read_b64 v[236:237], v223 offset:34304
	ds_read_b64 v[238:239], v223 offset:34320
	ds_read_b64 v[240:241], v223 offset:38656
	ds_read_b64 v[242:243], v223 offset:38672
	ds_read_b64 v[244:245], v223 offset:25632
	ds_read_b64 v[246:247], v223 offset:25648
	v_cndmask_b32_e32 v249, v210, v249, vcc
	v_lshlrev_b32_e32 v249, 2, v249
	s_nop 1
	v_max_f32_e32 v0, v96, v80
	v_max3_f32 v0, v0, v97, v81
	v_max3_f32 v0, v0, v98, v82
	v_max3_f32 v0, v0, v99, v83
	v_max3_f32 v0, v0, v100, v84
	v_max3_f32 v0, v0, v101, v85
	v_max3_f32 v0, v0, v102, v86
	v_max3_f32 v0, v0, v103, v87
	v_max3_f32 v0, v0, v104, v88
	v_max3_f32 v0, v0, v105, v89
	v_max3_f32 v0, v0, v106, v90
	v_max3_f32 v0, v0, v107, v91
	v_max3_f32 v0, v0, v108, v92
	v_max3_f32 v0, v0, v109, v93
	v_max3_f32 v0, v0, v110, v94
	v_max3_f32 v0, v0, v111, v95
	ds_bpermute_b32 v248, v249, v0
	s_waitcnt lgkmcnt(0)
	v_max_f32_e32 v0, v0, v248
	v_max_f32_e32 v248, v226, v226
	v_max_f32_e32 v0, v0, v0
	v_max_f32_e32 v2, v248, v0
	v_sub_f32_e32 v0, v226, v2
	v_exp_f32_e32 v0, v0
	s_nop 0
	v_cmp_neq_f32_e32 vcc, 1.0, v0
	s_cbranch_vccz .Lmla_norescale_a
	v_pk_mul_f32 v[78:79], v[78:79], v[0:1] op_sel_hi:[1,0]
	v_pk_mul_f32 v[76:77], v[76:77], v[0:1] op_sel_hi:[1,0]
	v_pk_mul_f32 v[74:75], v[74:75], v[0:1] op_sel_hi:[1,0]
	v_pk_mul_f32 v[72:73], v[72:73], v[0:1] op_sel_hi:[1,0]
	v_pk_mul_f32 v[70:71], v[70:71], v[0:1] op_sel_hi:[1,0]
	v_pk_mul_f32 v[68:69], v[68:69], v[0:1] op_sel_hi:[1,0]
	v_pk_mul_f32 v[66:67], v[66:67], v[0:1] op_sel_hi:[1,0]
	v_pk_mul_f32 v[64:65], v[64:65], v[0:1] op_sel_hi:[1,0]
	v_pk_mul_f32 v[62:63], v[62:63], v[0:1] op_sel_hi:[1,0]
	v_pk_mul_f32 v[60:61], v[60:61], v[0:1] op_sel_hi:[1,0]
	v_pk_mul_f32 v[58:59], v[58:59], v[0:1] op_sel_hi:[1,0]
	v_pk_mul_f32 v[56:57], v[56:57], v[0:1] op_sel_hi:[1,0]
	v_pk_mul_f32 v[54:55], v[54:55], v[0:1] op_sel_hi:[1,0]
	v_pk_mul_f32 v[52:53], v[52:53], v[0:1] op_sel_hi:[1,0]
	v_pk_mul_f32 v[50:51], v[50:51], v[0:1] op_sel_hi:[1,0]
	v_pk_mul_f32 v[48:49], v[48:49], v[0:1] op_sel_hi:[1,0]
	v_pk_mul_f32 v[46:47], v[46:47], v[0:1] op_sel_hi:[1,0]
	v_pk_mul_f32 v[44:45], v[44:45], v[0:1] op_sel_hi:[1,0]
	v_pk_mul_f32 v[42:43], v[42:43], v[0:1] op_sel_hi:[1,0]
	v_pk_mul_f32 v[40:41], v[40:41], v[0:1] op_sel_hi:[1,0]
	v_pk_mul_f32 v[38:39], v[38:39], v[0:1] op_sel_hi:[1,0]
	v_pk_mul_f32 v[36:37], v[36:37], v[0:1] op_sel_hi:[1,0]
	v_pk_mul_f32 v[34:35], v[34:35], v[0:1] op_sel_hi:[1,0]
	v_pk_mul_f32 v[32:33], v[32:33], v[0:1] op_sel_hi:[1,0]
	v_pk_mul_f32 v[30:31], v[30:31], v[0:1] op_sel_hi:[1,0]
	v_pk_mul_f32 v[28:29], v[28:29], v[0:1] op_sel_hi:[1,0]
	v_pk_mul_f32 v[26:27], v[26:27], v[0:1] op_sel_hi:[1,0]
	v_pk_mul_f32 v[24:25], v[24:25], v[0:1] op_sel_hi:[1,0]
	v_pk_mul_f32 v[22:23], v[22:23], v[0:1] op_sel_hi:[1,0]
	v_pk_mul_f32 v[20:21], v[20:21], v[0:1] op_sel_hi:[1,0]
	v_pk_mul_f32 v[18:19], v[18:19], v[0:1] op_sel_hi:[1,0]
	v_pk_mul_f32 v[16:17], v[16:17], v[0:1] op_sel_hi:[1,0]
	.Lmla_norescale_a:
	v_sub_f32_e32 v248, v96, v2
	v_exp_f32_e32 v96, v248
	v_sub_f32_e32 v249, v97, v2
	v_exp_f32_e32 v97, v249
	v_sub_f32_e32 v248, v98, v2
	v_exp_f32_e32 v98, v248
	v_sub_f32_e32 v249, v99, v2
	v_exp_f32_e32 v99, v249
	v_sub_f32_e32 v248, v100, v2
	v_exp_f32_e32 v100, v248
	v_sub_f32_e32 v249, v101, v2
	v_exp_f32_e32 v101, v249
	v_sub_f32_e32 v248, v102, v2
	v_exp_f32_e32 v102, v248
	v_sub_f32_e32 v249, v103, v2
	v_exp_f32_e32 v103, v249
	s_nop 0
	v_cvt_pk_bf16_f32 v8, v96, v97
	v_cvt_pk_bf16_f32 v9, v98, v99
	v_cvt_pk_bf16_f32 v10, v100, v101
	v_cvt_pk_bf16_f32 v11, v102, v103
	v_sub_f32_e32 v248, v104, v2
	v_exp_f32_e32 v104, v248
	v_mfma_f32_32x32x16_bf16 v[64:79], v[228:231], v[8:11], v[64:79]
	ds_read_b64 v[228:229], v223 offset:29984
	ds_read_b64 v[230:231], v223 offset:30000
	v_sub_f32_e32 v249, v105, v2
	v_exp_f32_e32 v105, v249
	v_mfma_f32_32x32x16_bf16 v[48:63], v[232:235], v[8:11], v[48:63]
	ds_read_b64 v[232:233], v223 offset:34336
	ds_read_b64 v[234:235], v223 offset:34352
	v_sub_f32_e32 v248, v106, v2
	v_exp_f32_e32 v106, v248
	v_sub_f32_e32 v249, v107, v2
	v_exp_f32_e32 v107, v249
	v_mfma_f32_32x32x16_bf16 v[32:47], v[236:239], v[8:11], v[32:47]
	ds_read_b64 v[236:237], v223 offset:38688
	ds_read_b64 v[238:239], v223 offset:38704
	v_sub_f32_e32 v248, v108, v2
	v_exp_f32_e32 v108, v248
	v_sub_f32_e32 v249, v109, v2
	v_exp_f32_e32 v109, v249
	v_mfma_f32_32x32x16_bf16 v[16:31], v[240:243], v[8:11], v[16:31]
	ds_read_b64 v[240:241], v223 offset:25664
	ds_read_b64 v[242:243], v223 offset:25680
	v_sub_f32_e32 v248, v110, v2
	v_exp_f32_e32 v110, v248
	v_sub_f32_e32 v249, v111, v2
	v_exp_f32_e32 v111, v249
	s_nop 0
	v_cvt_pk_bf16_f32 v4, v104, v105
	v_cvt_pk_bf16_f32 v5, v106, v107
	v_cvt_pk_bf16_f32 v6, v108, v109
	v_cvt_pk_bf16_f32 v7, v110, v111
	s_nop 1
	v_mfma_f32_32x32x16_bf16 v[64:79], v[244:247], v[4:7], v[64:79]
	ds_read_b64 v[244:245], v223 offset:30016
	ds_read_b64 v[246:247], v223 offset:30032
	v_sub_f32_e32 v248, v80, v2
	v_exp_f32_e32 v80, v248
	v_sub_f32_e32 v249, v81, v2
	v_exp_f32_e32 v81, v249
	s_waitcnt lgkmcnt(8)
	v_mfma_f32_32x32x16_bf16 v[48:63], v[228:231], v[4:7], v[48:63]
	ds_read_b64 v[228:229], v223 offset:34368
	ds_read_b64 v[230:231], v223 offset:34384
	v_sub_f32_e32 v248, v82, v2
	v_exp_f32_e32 v82, v248
	v_sub_f32_e32 v249, v83, v2
	v_exp_f32_e32 v83, v249
	s_waitcnt lgkmcnt(8)
	v_mfma_f32_32x32x16_bf16 v[32:47], v[232:235], v[4:7], v[32:47]
	ds_read_b64 v[232:233], v223 offset:38720
	ds_read_b64 v[234:235], v223 offset:38736
	v_sub_f32_e32 v248, v84, v2
	v_exp_f32_e32 v84, v248
	v_sub_f32_e32 v249, v85, v2
	v_exp_f32_e32 v85, v249
	s_waitcnt lgkmcnt(8)
	v_mfma_f32_32x32x16_bf16 v[16:31], v[236:239], v[4:7], v[16:31]
	ds_read_b64 v[236:237], v223 offset:25696
	ds_read_b64 v[238:239], v223 offset:25712
	v_sub_f32_e32 v248, v86, v2
	v_exp_f32_e32 v86, v248
	v_sub_f32_e32 v249, v87, v2
	v_exp_f32_e32 v87, v249
	s_nop 0
	v_cvt_pk_bf16_f32 v12, v80, v81
	v_cvt_pk_bf16_f32 v13, v82, v83
	v_cvt_pk_bf16_f32 v14, v84, v85
	v_cvt_pk_bf16_f32 v15, v86, v87
	s_nop 1
	s_waitcnt lgkmcnt(8)
	v_mfma_f32_32x32x16_bf16 v[64:79], v[240:243], v[12:15], v[64:79]
	ds_read_b64 v[240:241], v223 offset:30048
	ds_read_b64 v[242:243], v223 offset:30064
	v_sub_f32_e32 v248, v88, v2
	v_exp_f32_e32 v88, v248
	v_sub_f32_e32 v249, v89, v2
	v_exp_f32_e32 v89, v249
	s_waitcnt lgkmcnt(8)
	v_mfma_f32_32x32x16_bf16 v[48:63], v[244:247], v[12:15], v[48:63]
	ds_read_b64 v[244:245], v223 offset:34400
	ds_read_b64 v[246:247], v223 offset:34416
	v_sub_f32_e32 v248, v90, v2
	v_exp_f32_e32 v90, v248
	v_sub_f32_e32 v249, v91, v2
	v_exp_f32_e32 v91, v249
	s_waitcnt lgkmcnt(8)
	v_mfma_f32_32x32x16_bf16 v[32:47], v[228:231], v[12:15], v[32:47]
	ds_read_b64 v[228:229], v223 offset:38752
	ds_read_b64 v[230:231], v223 offset:38768
	v_sub_f32_e32 v248, v92, v2
	v_exp_f32_e32 v92, v248
	v_sub_f32_e32 v249, v93, v2
	v_exp_f32_e32 v93, v249
	s_waitcnt lgkmcnt(8)
	v_mfma_f32_32x32x16_bf16 v[16:31], v[232:235], v[12:15], v[16:31]
	v_sub_f32_e32 v248, v94, v2
	v_exp_f32_e32 v94, v248
	v_sub_f32_e32 v249, v95, v2
	v_exp_f32_e32 v95, v249
	s_nop 0
	v_cvt_pk_bf16_f32 v8, v88, v89
	v_cvt_pk_bf16_f32 v9, v90, v91
	v_cvt_pk_bf16_f32 v10, v92, v93
	v_cvt_pk_bf16_f32 v11, v94, v95
	s_nop 1
	s_waitcnt lgkmcnt(6)
	v_mfma_f32_32x32x16_bf16 v[64:79], v[236:239], v[8:11], v[64:79]
	v_add_f32_e32 v3, v80, v96
	v_add_f32_e32 v248, v81, v97
	v_add_f32_e32 v3, v248, v3
	v_add_f32_e32 v249, v82, v98
	v_add_f32_e32 v3, v249, v3
	v_add_f32_e32 v248, v83, v99
	v_add_f32_e32 v3, v248, v3
	v_add_f32_e32 v249, v84, v100
	s_waitcnt lgkmcnt(4)
	v_mfma_f32_32x32x16_bf16 v[48:63], v[240:243], v[8:11], v[48:63]
	v_add_f32_e32 v3, v249, v3
	v_add_f32_e32 v248, v85, v101
	v_add_f32_e32 v3, v248, v3
	v_add_f32_e32 v249, v86, v102
	v_add_f32_e32 v3, v249, v3
	v_add_f32_e32 v248, v87, v103
	v_add_f32_e32 v3, v248, v3
	v_add_f32_e32 v249, v88, v104
	s_waitcnt lgkmcnt(2)
	v_mfma_f32_32x32x16_bf16 v[32:47], v[244:247], v[8:11], v[32:47]
	v_add_f32_e32 v3, v249, v3
	v_add_f32_e32 v248, v89, v105
	v_add_f32_e32 v3, v248, v3
	v_add_f32_e32 v249, v90, v106
	v_add_f32_e32 v3, v249, v3
	v_add_f32_e32 v248, v91, v107
	v_add_f32_e32 v3, v248, v3
	v_add_f32_e32 v249, v92, v108
	s_waitcnt lgkmcnt(0)
	v_mfma_f32_32x32x16_bf16 v[16:31], v[228:231], v[8:11], v[16:31]
	v_add_f32_e32 v3, v249, v3
	v_add_f32_e32 v248, v93, v109
	v_add_f32_e32 v3, v248, v3
	v_add_f32_e32 v249, v94, v110
	v_add_f32_e32 v3, v249, v3
	v_add_f32_e32 v248, v95, v111
	v_add_f32_e32 v3, v248, v3
	v_fmac_f32_e32 v3, v221, v0
	v_mov_b32_e32 v221, v3
	s_branch .LBB0_1563

.LBB0_1563:
	v_min_u32_e32 v0, s46, v205
	v_mad_u64_u32 v[4:5], s[50:51], v0, s30, v[208:209]
	v_lshlrev_b32_e32 v0, 6, v0
	s_waitcnt lgkmcnt(0)
	s_barrier
	ds_write_b128 v216, v[172:175]
	ds_write_b128 v217, v[184:187]
	ds_write_b128 v218, v[192:195]
	v_lshl_add_u64 v[6:7], v[0:1], 1, v[206:207]
	ds_write2_b64 v219, v[176:177], v[178:179] offset1:1
	s_waitcnt vmcnt(5)
	ds_write2_b64 v220, v[196:197], v[198:199] offset1:1
	v_add_co_u32_e32 v8, vcc, 0x2000, v4
	s_nop 1
	v_addc_co_u32_e32 v9, vcc, 0, v5, vcc
	v_add_co_u32_e32 v10, vcc, 0x4000, v4
	s_nop 1
	v_addc_co_u32_e32 v11, vcc, 0, v5, vcc
	global_load_dwordx4 v[184:187], v[8:9], off
	global_load_dwordx4 v[192:195], v[10:11], off
	global_load_dwordx4 v[172:175], v[4:5], off
	global_load_dwordx4 v[176:179], v[6:7], off
	v_add_co_u32_e32 v4, vcc, 0x310000, v6
	s_nop 1
	v_addc_co_u32_e32 v5, vcc, 0, v7, vcc
	global_load_dwordx4 v[196:199], v[4:5], off
	s_add_i32 s47, s47, 1
	s_cmp_ge_i32 s47, s43
	s_cbranch_scc1 .LBB0_1556
	ds_read_b128 v[4:7], v225 offset:43008
	ds_read_b128 v[8:11], v225 offset:55808
	ds_read_b128 v[12:15], v225 offset:43040
	ds_read_b128 v[228:231], v225 offset:55840
	ds_read_b128 v[232:235], v225 offset:43072
	ds_read_b128 v[236:239], v225 offset:55872
	ds_read_b128 v[240:243], v225 offset:43104
	s_waitcnt lgkmcnt(6)
	v_mfma_f32_32x32x16_bf16 v[96:111], v[4:7], v[156:159], 0
	ds_read_b128 v[244:247], v225 offset:55904
	s_waitcnt lgkmcnt(6)
	v_mfma_f32_32x32x16_bf16 v[80:95], v[8:11], v[156:159], 0
	ds_read_b128 v[4:7], v225 offset:43136
	s_waitcnt lgkmcnt(6)
	v_mfma_f32_32x32x16_bf16 v[96:111], v[12:15], v[152:155], v[96:111]
	ds_read_b128 v[8:11], v225 offset:55936
	s_waitcnt lgkmcnt(6)
	v_mfma_f32_32x32x16_bf16 v[80:95], v[228:231], v[152:155], v[80:95]
	ds_read_b128 v[12:15], v225 offset:43168
	s_waitcnt lgkmcnt(6)
	v_mfma_f32_32x32x16_bf16 v[96:111], v[232:235], v[148:151], v[96:111]
	ds_read_b128 v[228:231], v225 offset:55968
	s_waitcnt lgkmcnt(6)
	v_mfma_f32_32x32x16_bf16 v[80:95], v[236:239], v[148:151], v[80:95]
	ds_read_b128 v[232:235], v225 offset:43200
	s_waitcnt lgkmcnt(6)
	v_mfma_f32_32x32x16_bf16 v[96:111], v[240:243], v[144:147], v[96:111]
	ds_read_b128 v[236:239], v225 offset:56000
	s_waitcnt lgkmcnt(6)
	v_mfma_f32_32x32x16_bf16 v[80:95], v[244:247], v[144:147], v[80:95]
	ds_read_b128 v[240:243], v225 offset:43232
	s_waitcnt lgkmcnt(6)
	v_mfma_f32_32x32x16_bf16 v[96:111], v[4:7], v[140:143], v[96:111]
	ds_read_b128 v[244:247], v225 offset:56032
	s_waitcnt lgkmcnt(6)
	v_mfma_f32_32x32x16_bf16 v[80:95], v[8:11], v[140:143], v[80:95]
	ds_read_b128 v[4:7], v225 offset:43264
	s_waitcnt lgkmcnt(6)
	v_mfma_f32_32x32x16_bf16 v[96:111], v[12:15], v[136:139], v[96:111]
	ds_read_b128 v[8:11], v225 offset:56064
	s_waitcnt lgkmcnt(6)
	v_mfma_f32_32x32x16_bf16 v[80:95], v[228:231], v[136:139], v[80:95]
	ds_read_b128 v[12:15], v225 offset:43296
	s_waitcnt lgkmcnt(6)
	v_mfma_f32_32x32x16_bf16 v[96:111], v[232:235], v[132:135], v[96:111]
	ds_read_b128 v[228:231], v225 offset:56096
	s_waitcnt lgkmcnt(6)
	v_mfma_f32_32x32x16_bf16 v[80:95], v[236:239], v[132:135], v[80:95]
	ds_read_b128 v[232:235], v225 offset:43328
	s_waitcnt lgkmcnt(6)
	v_mfma_f32_32x32x16_bf16 v[96:111], v[240:243], v[128:131], v[96:111]
	ds_read_b128 v[236:239], v225 offset:56128
	s_waitcnt lgkmcnt(6)
	v_mfma_f32_32x32x16_bf16 v[80:95], v[244:247], v[128:131], v[80:95]
	ds_read_b128 v[240:243], v225 offset:43360
	s_waitcnt lgkmcnt(6)
	v_mfma_f32_32x32x16_bf16 v[96:111], v[4:7], v[124:127], v[96:111]
	ds_read_b128 v[244:247], v225 offset:56160
	s_waitcnt lgkmcnt(6)
	v_mfma_f32_32x32x16_bf16 v[80:95], v[8:11], v[124:127], v[80:95]
	s_waitcnt lgkmcnt(5)
	v_mfma_f32_32x32x16_bf16 v[96:111], v[12:15], v[120:123], v[96:111]
	s_waitcnt lgkmcnt(4)
	v_mfma_f32_32x32x16_bf16 v[80:95], v[228:231], v[120:123], v[80:95]
	s_waitcnt lgkmcnt(3)
	v_mfma_f32_32x32x16_bf16 v[96:111], v[232:235], v[116:119], v[96:111]
	s_waitcnt lgkmcnt(2)
	v_mfma_f32_32x32x16_bf16 v[80:95], v[236:239], v[116:119], v[80:95]
	s_waitcnt lgkmcnt(1)
	v_mfma_f32_32x32x16_bf16 v[96:111], v[240:243], v[112:115], v[96:111]
	s_waitcnt lgkmcnt(0)
	v_mfma_f32_32x32x16_bf16 v[80:95], v[244:247], v[112:115], v[80:95]
	v_and_b32_e32 v248, 64, v210
	v_xor_b32_e32 v249, 32, v210
	v_add_u32_e32 v248, 64, v248
	v_cmp_lt_i32_e32 vcc, v249, v248
	ds_read_b64 v[228:229], v224 offset:0
	ds_read_b64 v[230:231], v224 offset:16
	ds_read_b64 v[232:233], v224 offset:4352
	ds_read_b64 v[234:235], v224 offset:4368
	ds_read_b64 v[236:237], v224 offset:8704
	ds_read_b64 v[238:239], v224 offset:8720
	ds_read_b64 v[240:241], v224 offset:13056
	ds_read_b64 v[242:243], v224 offset:13072
	ds_read_b64 v[244:245], v224 offset:32
	ds_read_b64 v[246:247], v224 offset:48
	v_cndmask_b32_e32 v249, v210, v249, vcc
	v_lshlrev_b32_e32 v249, 2, v249
	s_nop 1
	v_max_f32_e32 v0, v96, v80
	v_max3_f32 v0, v0, v97, v81
	v_max3_f32 v0, v0, v98, v82
	v_max3_f32 v0, v0, v99, v83
	v_max3_f32 v0, v0, v100, v84
	v_max3_f32 v0, v0, v101, v85
	v_max3_f32 v0, v0, v102, v86
	v_max3_f32 v0, v0, v103, v87
	v_max3_f32 v0, v0, v104, v88
	v_max3_f32 v0, v0, v105, v89
	v_max3_f32 v0, v0, v106, v90
	v_max3_f32 v0, v0, v107, v91
	v_max3_f32 v0, v0, v108, v92
	v_max3_f32 v0, v0, v109, v93
	v_max3_f32 v0, v0, v110, v94
	v_max3_f32 v0, v0, v111, v95
	ds_bpermute_b32 v248, v249, v0
	s_waitcnt lgkmcnt(0)
	v_max_f32_e32 v0, v0, v248
	v_max_f32_e32 v248, v2, v2
	v_max_f32_e32 v0, v0, v0
	v_max_f32_e32 v226, v248, v0
	v_sub_f32_e32 v0, v2, v226
	v_exp_f32_e32 v0, v0
	s_nop 0
	v_cmp_neq_f32_e32 vcc, 1.0, v0
	s_cbranch_vccz .Lmla_norescale_b
	v_pk_mul_f32 v[78:79], v[78:79], v[0:1] op_sel_hi:[1,0]
	v_pk_mul_f32 v[76:77], v[76:77], v[0:1] op_sel_hi:[1,0]
	v_pk_mul_f32 v[74:75], v[74:75], v[0:1] op_sel_hi:[1,0]
	v_pk_mul_f32 v[72:73], v[72:73], v[0:1] op_sel_hi:[1,0]
	v_pk_mul_f32 v[70:71], v[70:71], v[0:1] op_sel_hi:[1,0]
	v_pk_mul_f32 v[68:69], v[68:69], v[0:1] op_sel_hi:[1,0]
	v_pk_mul_f32 v[66:67], v[66:67], v[0:1] op_sel_hi:[1,0]
	v_pk_mul_f32 v[64:65], v[64:65], v[0:1] op_sel_hi:[1,0]
	v_pk_mul_f32 v[62:63], v[62:63], v[0:1] op_sel_hi:[1,0]
	v_pk_mul_f32 v[60:61], v[60:61], v[0:1] op_sel_hi:[1,0]
	v_pk_mul_f32 v[58:59], v[58:59], v[0:1] op_sel_hi:[1,0]
	v_pk_mul_f32 v[56:57], v[56:57], v[0:1] op_sel_hi:[1,0]
	v_pk_mul_f32 v[54:55], v[54:55], v[0:1] op_sel_hi:[1,0]
	v_pk_mul_f32 v[52:53], v[52:53], v[0:1] op_sel_hi:[1,0]
	v_pk_mul_f32 v[50:51], v[50:51], v[0:1] op_sel_hi:[1,0]
	v_pk_mul_f32 v[48:49], v[48:49], v[0:1] op_sel_hi:[1,0]
	v_pk_mul_f32 v[46:47], v[46:47], v[0:1] op_sel_hi:[1,0]
	v_pk_mul_f32 v[44:45], v[44:45], v[0:1] op_sel_hi:[1,0]
	v_pk_mul_f32 v[42:43], v[42:43], v[0:1] op_sel_hi:[1,0]
	v_pk_mul_f32 v[40:41], v[40:41], v[0:1] op_sel_hi:[1,0]
	v_pk_mul_f32 v[38:39], v[38:39], v[0:1] op_sel_hi:[1,0]
	v_pk_mul_f32 v[36:37], v[36:37], v[0:1] op_sel_hi:[1,0]
	v_pk_mul_f32 v[34:35], v[34:35], v[0:1] op_sel_hi:[1,0]
	v_pk_mul_f32 v[32:33], v[32:33], v[0:1] op_sel_hi:[1,0]
	v_pk_mul_f32 v[30:31], v[30:31], v[0:1] op_sel_hi:[1,0]
	v_pk_mul_f32 v[28:29], v[28:29], v[0:1] op_sel_hi:[1,0]
	v_pk_mul_f32 v[26:27], v[26:27], v[0:1] op_sel_hi:[1,0]
	v_pk_mul_f32 v[24:25], v[24:25], v[0:1] op_sel_hi:[1,0]
	v_pk_mul_f32 v[22:23], v[22:23], v[0:1] op_sel_hi:[1,0]
	v_pk_mul_f32 v[20:21], v[20:21], v[0:1] op_sel_hi:[1,0]
	v_pk_mul_f32 v[18:19], v[18:19], v[0:1] op_sel_hi:[1,0]
	v_pk_mul_f32 v[16:17], v[16:17], v[0:1] op_sel_hi:[1,0]
	.Lmla_norescale_b:
	v_sub_f32_e32 v248, v96, v226
	v_exp_f32_e32 v96, v248
	v_sub_f32_e32 v249, v97, v226
	v_exp_f32_e32 v97, v249
	v_sub_f32_e32 v248, v98, v226
	v_exp_f32_e32 v98, v248
	v_sub_f32_e32 v249, v99, v226
	v_exp_f32_e32 v99, v249
	v_sub_f32_e32 v248, v100, v226
	v_exp_f32_e32 v100, v248
	v_sub_f32_e32 v249, v101, v226
	v_exp_f32_e32 v101, v249
	v_sub_f32_e32 v248, v102, v226
	v_exp_f32_e32 v102, v248
	v_sub_f32_e32 v249, v103, v226
	v_exp_f32_e32 v103, v249
	s_nop 0
	v_cvt_pk_bf16_f32 v8, v96, v97
	v_cvt_pk_bf16_f32 v9, v98, v99
	v_cvt_pk_bf16_f32 v10, v100, v101
	v_cvt_pk_bf16_f32 v11, v102, v103
	v_sub_f32_e32 v248, v104, v226
	v_exp_f32_e32 v104, v248
	v_mfma_f32_32x32x16_bf16 v[64:79], v[228:231], v[8:11], v[64:79]
	ds_read_b64 v[228:229], v224 offset:4384
	ds_read_b64 v[230:231], v224 offset:4400
	v_sub_f32_e32 v249, v105, v226
	v_exp_f32_e32 v105, v249
	v_mfma_f32_32x32x16_bf16 v[48:63], v[232:235], v[8:11], v[48:63]
	ds_read_b64 v[232:233], v224 offset:8736
	ds_read_b64 v[234:235], v224 offset:8752
	v_sub_f32_e32 v248, v106, v226
	v_exp_f32_e32 v106, v248
	v_sub_f32_e32 v249, v107, v226
	v_exp_f32_e32 v107, v249
	v_mfma_f32_32x32x16_bf16 v[32:47], v[236:239], v[8:11], v[32:47]
	ds_read_b64 v[236:237], v224 offset:13088
	ds_read_b64 v[238:239], v224 offset:13104
	v_sub_f32_e32 v248, v108, v226
	v_exp_f32_e32 v108, v248
	v_sub_f32_e32 v249, v109, v226
	v_exp_f32_e32 v109, v249
	v_mfma_f32_32x32x16_bf16 v[16:31], v[240:243], v[8:11], v[16:31]
	ds_read_b64 v[240:241], v224 offset:64
	ds_read_b64 v[242:243], v224 offset:80
	v_sub_f32_e32 v248, v110, v226
	v_exp_f32_e32 v110, v248
	v_sub_f32_e32 v249, v111, v226
	v_exp_f32_e32 v111, v249
	s_nop 0
	v_cvt_pk_bf16_f32 v4, v104, v105
	v_cvt_pk_bf16_f32 v5, v106, v107
	v_cvt_pk_bf16_f32 v6, v108, v109
	v_cvt_pk_bf16_f32 v7, v110, v111
	s_nop 1
	v_mfma_f32_32x32x16_bf16 v[64:79], v[244:247], v[4:7], v[64:79]
	ds_read_b64 v[244:245], v224 offset:4416
	ds_read_b64 v[246:247], v224 offset:4432
	v_sub_f32_e32 v248, v80, v226
	v_exp_f32_e32 v80, v248
	v_sub_f32_e32 v249, v81, v226
	v_exp_f32_e32 v81, v249
	s_waitcnt lgkmcnt(8)
	v_mfma_f32_32x32x16_bf16 v[48:63], v[228:231], v[4:7], v[48:63]
	ds_read_b64 v[228:229], v224 offset:8768
	ds_read_b64 v[230:231], v224 offset:8784
	v_sub_f32_e32 v248, v82, v226
	v_exp_f32_e32 v82, v248
	v_sub_f32_e32 v249, v83, v226
	v_exp_f32_e32 v83, v249
	s_waitcnt lgkmcnt(8)
	v_mfma_f32_32x32x16_bf16 v[32:47], v[232:235], v[4:7], v[32:47]
	ds_read_b64 v[232:233], v224 offset:13120
	ds_read_b64 v[234:235], v224 offset:13136
	v_sub_f32_e32 v248, v84, v226
	v_exp_f32_e32 v84, v248
	v_sub_f32_e32 v249, v85, v226
	v_exp_f32_e32 v85, v249
	s_waitcnt lgkmcnt(8)
	v_mfma_f32_32x32x16_bf16 v[16:31], v[236:239], v[4:7], v[16:31]
	ds_read_b64 v[236:237], v224 offset:96
	ds_read_b64 v[238:239], v224 offset:112
	v_sub_f32_e32 v248, v86, v226
	v_exp_f32_e32 v86, v248
	v_sub_f32_e32 v249, v87, v226
	v_exp_f32_e32 v87, v249
	s_nop 0
	v_cvt_pk_bf16_f32 v12, v80, v81
	v_cvt_pk_bf16_f32 v13, v82, v83
	v_cvt_pk_bf16_f32 v14, v84, v85
	v_cvt_pk_bf16_f32 v15, v86, v87
	s_nop 1
	s_waitcnt lgkmcnt(8)
	v_mfma_f32_32x32x16_bf16 v[64:79], v[240:243], v[12:15], v[64:79]
	ds_read_b64 v[240:241], v224 offset:4448
	ds_read_b64 v[242:243], v224 offset:4464
	v_sub_f32_e32 v248, v88, v226
	v_exp_f32_e32 v88, v248
	v_sub_f32_e32 v249, v89, v226
	v_exp_f32_e32 v89, v249
	s_waitcnt lgkmcnt(8)
	v_mfma_f32_32x32x16_bf16 v[48:63], v[244:247], v[12:15], v[48:63]
	ds_read_b64 v[244:245], v224 offset:8800
	ds_read_b64 v[246:247], v224 offset:8816
	v_sub_f32_e32 v248, v90, v226
	v_exp_f32_e32 v90, v248
	v_sub_f32_e32 v249, v91, v226
	v_exp_f32_e32 v91, v249
	s_waitcnt lgkmcnt(8)
	v_mfma_f32_32x32x16_bf16 v[32:47], v[228:231], v[12:15], v[32:47]
	ds_read_b64 v[228:229], v224 offset:13152
	ds_read_b64 v[230:231], v224 offset:13168
	v_sub_f32_e32 v248, v92, v226
	v_exp_f32_e32 v92, v248
	v_sub_f32_e32 v249, v93, v226
	v_exp_f32_e32 v93, v249
	s_waitcnt lgkmcnt(8)
	v_mfma_f32_32x32x16_bf16 v[16:31], v[232:235], v[12:15], v[16:31]
	v_sub_f32_e32 v248, v94, v226
	v_exp_f32_e32 v94, v248
	v_sub_f32_e32 v249, v95, v226
	v_exp_f32_e32 v95, v249
	s_nop 0
	v_cvt_pk_bf16_f32 v8, v88, v89
	v_cvt_pk_bf16_f32 v9, v90, v91
	v_cvt_pk_bf16_f32 v10, v92, v93
	v_cvt_pk_bf16_f32 v11, v94, v95
	s_nop 1
	s_waitcnt lgkmcnt(6)
	v_mfma_f32_32x32x16_bf16 v[64:79], v[236:239], v[8:11], v[64:79]
	v_add_f32_e32 v3, v80, v96
	v_add_f32_e32 v248, v81, v97
	v_add_f32_e32 v3, v248, v3
	v_add_f32_e32 v249, v82, v98
	v_add_f32_e32 v3, v249, v3
	v_add_f32_e32 v248, v83, v99
	v_add_f32_e32 v3, v248, v3
	v_add_f32_e32 v249, v84, v100
	s_waitcnt lgkmcnt(4)
	v_mfma_f32_32x32x16_bf16 v[48:63], v[240:243], v[8:11], v[48:63]
	v_add_f32_e32 v3, v249, v3
	v_add_f32_e32 v248, v85, v101
	v_add_f32_e32 v3, v248, v3
	v_add_f32_e32 v249, v86, v102
	v_add_f32_e32 v3, v249, v3
	v_add_f32_e32 v248, v87, v103
	v_add_f32_e32 v3, v248, v3
	v_add_f32_e32 v249, v88, v104
	s_waitcnt lgkmcnt(2)
	v_mfma_f32_32x32x16_bf16 v[32:47], v[244:247], v[8:11], v[32:47]
	v_add_f32_e32 v3, v249, v3
	v_add_f32_e32 v248, v89, v105
	v_add_f32_e32 v3, v248, v3
	v_add_f32_e32 v249, v90, v106
	v_add_f32_e32 v3, v249, v3
	v_add_f32_e32 v248, v91, v107
	v_add_f32_e32 v3, v248, v3
	v_add_f32_e32 v249, v92, v108
	s_waitcnt lgkmcnt(0)
	v_mfma_f32_32x32x16_bf16 v[16:31], v[228:231], v[8:11], v[16:31]
	v_add_f32_e32 v3, v249, v3
	v_add_f32_e32 v248, v93, v109
	v_add_f32_e32 v3, v248, v3
	v_add_f32_e32 v249, v94, v110
	v_add_f32_e32 v3, v249, v3
	v_add_f32_e32 v248, v95, v111
	v_add_f32_e32 v3, v248, v3
	v_fmac_f32_e32 v3, v221, v0
	v_mov_b32_e32 v221, v3
	s_branch .LBB0_1557

; #define G_STORE(BUF) do { char* l_ = lds + (BUF) * STAGE + wofs; \
;         *(uint4*)(l_) = ra0; *(uint4*)(l_ + 8192) = ra1; *(uint4*)(l_ + 16384) = ra2; if (MT == 4) *(uint4*)(l_ + 24576) = ra3; \
;         *(uint4*)(l_ + ABYTES) = rb0; *(uint4*)(l_ + ABYTES + 8192) = rb1; *(uint4*)(l_ + ABYTES + 16384) = rb2; *(uint4*)(l_ + ABYTES + 24576) = rb3; } while (0)
; template <int MT, bool PIN, class Epi>
; __device__ __forceinline__ void gemm_phase(const Params& P, const bf16_t* __restrict__ A, const bf16_t* __restrict__ Bt, int nM, int nN, int K, const Epi epi, char* lds) {
;     ...
;         const long L = (long)it * G + blockIdx.x; if (L >= nT) break;
;         int pm, pn; map_tile((int)L, nM, nN, pm, pn);
;         const char* Ab = (const char*)(A + (size_t)pm * BM * K);
;         const char* Bb = (const char*)(Bt + (size_t)pn * 256 * K);
;         const unsigned toff = (unsigned)(srow * K + sch * 8) * 2u, rs = (unsigned)K * 128u;
;         uint4 ra0, ra1, ra2, ra3, rb0, rb1, rb2, rb3;
;     ...
;         G_LOAD(0);
;         f32x16 acc[MT][2];
; #pragma unroll
;         for (int a = 0; a < MT; ++a)
; #pragma unroll
;             for (int b = 0; b < 2; ++b)
; #pragma unroll
;                 for (int e = 0; e < 16; ++e) acc[a][b][e] = 0.f;
;         bf16x8 fa[2][MT], fb[2][2];
;         __syncthreads();
;         G_STORE(0);
;         G_LOAD(1);
;         __syncthreads();
.LBB0_2401:
	s_mul_i32 s0, s10, s33
	s_mul_hi_u32 s1, s10, s84
	s_add_i32 s1, s1, s0
	s_mul_i32 s0, s10, s84
	s_add_u32 s0, s0, s2
	s_addc_u32 s1, s1, 0
	v_cmp_gt_i64_e32 vcc, s[0:1], v[140:141]
	s_mov_b64 s[4:5], -1
	s_cbranch_vccnz .LBB0_2400
	s_and_b32 s1, s0, 7
	s_mulk_i32 s1, 0x58
	s_ashr_i32 s0, s0, 3
	s_add_i32 s0, s1, s0
	s_ashr_i32 s1, s0, 31
	s_lshr_b32 s1, s1, 26
	s_add_i32 s1, s0, s1
	s_ashr_i32 s4, s1, 6
	s_lshl_b32 s4, s4, 3
	s_sub_i32 s5, 0x58, s4
	s_min_i32 s5, s5, 8
	s_abs_i32 s6, s5
	v_cvt_f32_u32_e32 v0, s6
	s_sub_i32 s14, 0, s6
	s_andn2_b32 s1, s1, 63
	s_sub_i32 s1, s0, s1
	v_rcp_iflag_f32_e32 v0, v0
	s_abs_i32 s0, s1
	s_xor_b32 s7, s1, s5
	s_ashr_i32 s7, s7, 31
	v_mul_f32_e32 v0, 0x4f7ffffe, v0
	v_cvt_u32_f32_e32 v0, v0
	s_nop 0
	v_readfirstlane_b32 s15, v0
	s_mul_i32 s14, s14, s15
	s_mul_hi_u32 s14, s15, s14
	s_add_i32 s15, s15, s14
	s_mul_hi_u32 s14, s0, s15
	s_mul_i32 s15, s14, s6
	s_sub_i32 s0, s0, s15
	s_add_i32 s16, s14, 1
	s_sub_i32 s15, s0, s6
	s_cmp_ge_u32 s0, s6
	s_cselect_b32 s14, s16, s14
	s_cselect_b32 s0, s15, s0
	s_add_i32 s15, s14, 1
	s_cmp_ge_u32 s0, s6
	s_cselect_b32 s0, s15, s14
	s_xor_b32 s0, s0, s7
	s_sub_i32 s0, s0, s7
	s_mul_i32 s5, s0, s5
	s_sub_i32 s14, s1, s5
	s_add_i32 s14, s14, s4
	s_mul_i32 s4, s14, 0xc0000
	s_mul_hi_i32 s1, s14, 0xc0000
	s_add_u32 s4, s90, s4
	s_addc_u32 s5, s91, s1
	s_ashr_i32 s1, s0, 31
	s_lshl_b64 s[6:7], s[0:1], 20
	s_add_u32 s6, s8, s6
	v_lshl_add_u64 v[28:29], s[4:5], 0, v[124:125]
	v_lshl_add_u64 v[0:1], s[4:5], 0, v[128:129]
	s_addc_u32 s7, s9, s7
	global_load_dwordx4 v[40:43], v[28:29], off
	global_load_dwordx4 v[44:47], v[0:1], off
	v_lshl_add_u64 v[0:1], s[4:5], 0, v[130:131]
	v_lshl_add_u64 v[30:31], s[6:7], 0, v[124:125]
	global_load_dwordx4 v[48:51], v[0:1], off
	global_load_dwordx4 v[52:55], v[30:31], off
	v_lshl_add_u64 v[0:1], s[6:7], 0, v[128:129]
	v_lshl_add_u64 v[2:3], s[6:7], 0, v[130:131]
	global_load_dwordx4 v[56:59], v[0:1], off
	global_load_dwordx4 v[60:63], v[2:3], off
	v_lshl_add_u64 v[0:1], s[6:7], 0, v[132:133]
	v_lshl_add_u64 v[32:33], s[4:5], 0, v[134:135]
	global_load_dwordx4 v[64:67], v[0:1], off
	v_lshl_add_u64 v[34:35], s[4:5], 0, v[136:137]
	v_lshl_add_u64 v[36:37], s[6:7], 0, v[134:135]
	v_lshl_add_u64 v[38:39], s[6:7], 0, v[136:137]
	v_lshl_add_u64 v[68:69], s[6:7], 0, v[138:139]
	s_barrier
	global_load_dwordx4 v[96:99], v[28:29], off offset:128
	global_load_dwordx4 v[100:103], v[32:33], off
	global_load_dwordx4 v[108:111], v[34:35], off
	global_load_dwordx4 v[104:107], v[30:31], off offset:128
	global_load_dwordx4 v[112:115], v[36:37], off
	global_load_dwordx4 v[116:119], v[38:39], off
	global_load_dwordx4 v[120:123], v[68:69], off
	global_load_dwordx4 v[212:215], v[28:29], off offset:256
	global_load_dwordx4 v[216:219], v[32:33], off offset:128
	global_load_dwordx4 v[220:223], v[34:35], off offset:128
	global_load_dwordx4 v[224:227], v[30:31], off offset:256
	global_load_dwordx4 v[228:231], v[36:37], off offset:128
	global_load_dwordx4 v[232:235], v[38:39], off offset:128
	global_load_dwordx4 v[236:239], v[68:69], off offset:128
	v_mov_b32_e32 v0, 0
	s_mov_b32 s15, 0
	s_movk_i32 s1, 0x180
	v_mov_b32_e32 v1, v0
	v_mov_b32_e32 v2, v0
	v_mov_b32_e32 v3, v0
	v_mov_b32_e32 v4, v0
	v_mov_b32_e32 v5, v0
	v_mov_b32_e32 v6, v0
	v_mov_b32_e32 v7, v0
	v_mov_b32_e32 v8, v0
	v_mov_b32_e32 v9, v0
	v_mov_b32_e32 v10, v0
	v_mov_b32_e32 v11, v0
	v_mov_b32_e32 v12, v0
	v_mov_b32_e32 v13, v0
	v_mov_b32_e32 v14, v0
	v_mov_b32_e32 v15, v0
	v_mov_b32_e32 v16, v0
	v_mov_b32_e32 v17, v0
	v_mov_b32_e32 v18, v0
	v_mov_b32_e32 v19, v0
	v_mov_b32_e32 v20, v0
	v_mov_b32_e32 v21, v0
	v_mov_b32_e32 v22, v0
	v_mov_b32_e32 v23, v0
	v_mov_b32_e32 v24, v0
	v_mov_b32_e32 v25, v0
	v_mov_b32_e32 v26, v0
	v_mov_b32_e32 v27, v0
	v_mov_b32_e32 v28, v0
	v_mov_b32_e32 v29, v0
	v_mov_b32_e32 v30, v0
	v_mov_b32_e32 v31, v0
	v_mov_b32_e32 v32, v0
	v_mov_b32_e32 v33, v0
	v_mov_b32_e32 v34, v0
	v_mov_b32_e32 v35, v0
	v_mov_b32_e32 v36, v0
	v_mov_b32_e32 v37, v0
	v_mov_b32_e32 v38, v0
	v_mov_b32_e32 v39, v0
	v_mov_b32_e32 v68, v0
	v_mov_b32_e32 v69, v0
	v_mov_b32_e32 v70, v0
	v_mov_b32_e32 v71, v0
	v_mov_b32_e32 v72, v0
	v_mov_b32_e32 v73, v0
	v_mov_b32_e32 v74, v0
	v_mov_b32_e32 v75, v0
	v_mov_b32_e32 v76, v0
	v_mov_b32_e32 v77, v0
	v_mov_b32_e32 v78, v0
	v_mov_b32_e32 v79, v0
	v_mov_b32_e32 v80, v0
	v_mov_b32_e32 v81, v0
	s_waitcnt vmcnt(20)
	ds_write_b128 v142, v[40:43]
	s_waitcnt vmcnt(19)
	ds_write_b128 v142, v[44:47] offset:8192
	s_waitcnt vmcnt(18)
	ds_write_b128 v142, v[48:51] offset:16384
	s_waitcnt vmcnt(17)
	ds_write_b128 v142, v[52:55] offset:24576
	s_waitcnt vmcnt(16)
	ds_write_b128 v142, v[56:59] offset:32768
	s_waitcnt vmcnt(15)
	ds_write_b128 v142, v[60:63] offset:40960
	s_waitcnt vmcnt(14)
	ds_write_b128 v142, v[64:67] offset:49152
	v_mov_b32_e32 v40, v0
	v_mov_b32_e32 v41, v0
	v_mov_b32_e32 v42, v0
	v_mov_b32_e32 v43, v0
	v_mov_b32_e32 v44, v0
	v_mov_b32_e32 v45, v0
	v_mov_b32_e32 v46, v0
	v_mov_b32_e32 v47, v0
	v_mov_b32_e32 v48, v0
	v_mov_b32_e32 v49, v0
	v_mov_b32_e32 v50, v0
	v_mov_b32_e32 v51, v0
	v_mov_b32_e32 v52, v0
	v_mov_b32_e32 v53, v0
	v_mov_b32_e32 v54, v0
	v_mov_b32_e32 v55, v0
	v_mov_b32_e32 v56, v0
	v_mov_b32_e32 v57, v0
	v_mov_b32_e32 v58, v0
	v_mov_b32_e32 v59, v0
	v_mov_b32_e32 v60, v0
	v_mov_b32_e32 v61, v0
	v_mov_b32_e32 v62, v0
	v_mov_b32_e32 v63, v0
	v_mov_b32_e32 v64, v0
	v_mov_b32_e32 v65, v0
	v_mov_b32_e32 v66, v0
	v_mov_b32_e32 v67, v0
	v_mov_b32_e32 v82, v0
	v_mov_b32_e32 v83, v0
	v_mov_b32_e32 v84, v0
	v_mov_b32_e32 v85, v0
	v_mov_b32_e32 v86, v0
	v_mov_b32_e32 v87, v0
	v_mov_b32_e32 v88, v0
	v_mov_b32_e32 v89, v0
	v_mov_b32_e32 v90, v0
	v_mov_b32_e32 v91, v0
	v_mov_b32_e32 v92, v0
	v_mov_b32_e32 v93, v0
	v_mov_b32_e32 v94, v0
	v_mov_b32_e32 v95, v0
	s_waitcnt lgkmcnt(0)
	s_barrier
.LBB0_2403:
	v_add_u32_e32 v180, v145, v143
	ds_read_b128 v[164:167], v144
	ds_read_b128 v[168:171], v144 offset:4096
	ds_read_b128 v[172:175], v144 offset:8192
	ds_read_b128 v[176:179], v180 offset:24576
	ds_read_b128 v[180:183], v180 offset:28672
	s_add_i32 s16, s15, 2
	s_min_u32 s17, s1, 0xf80
	s_add_i32 s98, s1, 0x80
	s_min_u32 s98, s98, 0xf80
	s_addk_i32 s1, 0x100
	v_add_u32_e32 v240, s17, v124
	v_add_u32_e32 v241, 0x40000, v240
	v_add_u32_e32 v242, 0x80000, v240
	v_add_u32_e32 v243, 0xc0000, v240
	s_waitcnt lgkmcnt(1)
	v_mfma_f32_32x32x16_bf16 v[80:95], v[164:167], v[176:179], v[80:95]
	v_add_u32_e32 v188, v145, v149
	v_add_u32_e32 v126, v154, v143
	s_waitcnt lgkmcnt(0)
	v_mfma_f32_32x32x16_bf16 v[64:79], v[164:167], v[180:183], v[64:79]
	ds_read_b128 v[164:167], v148
	s_waitcnt vmcnt(13)
	ds_write_b128 v142, v[96:99] offset:57344
	global_load_dwordx4 v[96:99], v240, s[4:5]
	v_mfma_f32_32x32x16_bf16 v[48:63], v[168:171], v[176:179], v[48:63]
	v_mfma_f32_32x32x16_bf16 v[32:47], v[168:171], v[180:183], v[32:47]
	s_waitcnt vmcnt(13)
	ds_write_b128 v146, v[100:103] offset:8192
	global_load_dwordx4 v[100:103], v241, s[4:5]
	v_mfma_f32_32x32x16_bf16 v[0:15], v[172:175], v[180:183], v[0:15]
	v_add_u32_e32 v180, v145, v147
	v_mfma_f32_32x32x16_bf16 v[16:31], v[172:175], v[176:179], v[16:31]
	ds_read_b128 v[168:171], v180 offset:24576
	ds_read_b128 v[172:175], v148 offset:4096
	ds_read_b128 v[176:179], v152 offset:8192
	ds_read_b128 v[180:183], v180 offset:28672
	ds_read_b128 v[184:187], v188 offset:24576
	s_waitcnt vmcnt(13)
	ds_write_b128 v146, v[108:111] offset:16384
	global_load_dwordx4 v[108:111], v242, s[4:5]
	s_waitcnt lgkmcnt(5)
	v_mfma_f32_32x32x16_bf16 v[80:95], v[164:167], v[168:171], v[80:95]
	s_waitcnt lgkmcnt(2)
	v_mfma_f32_32x32x16_bf16 v[64:79], v[164:167], v[180:183], v[64:79]
	s_waitcnt vmcnt(13)
	ds_write_b128 v146, v[104:107] offset:24576
	global_load_dwordx4 v[104:107], v240, s[6:7]
	v_mfma_f32_32x32x16_bf16 v[48:63], v[172:175], v[168:171], v[48:63]
	v_mfma_f32_32x32x16_bf16 v[32:47], v[172:175], v[180:183], v[32:47]
	ds_read_b128 v[164:167], v148 offset:8192
	ds_read_b128 v[172:175], v150
	s_waitcnt vmcnt(13)
	ds_write_b128 v146, v[112:115] offset:32768
	global_load_dwordx4 v[112:115], v241, s[6:7]
	s_waitcnt lgkmcnt(2)
	v_mfma_f32_32x32x16_bf16 v[16:31], v[164:167], v[168:171], v[16:31]
	v_mfma_f32_32x32x16_bf16 v[0:15], v[164:167], v[180:183], v[0:15]
	ds_read_b128 v[164:167], v188 offset:28672
	v_add_u32_e32 v188, v145, v151
	ds_read_b128 v[168:171], v188 offset:24576
	s_waitcnt vmcnt(13)
	ds_write_b128 v146, v[116:119] offset:40960
	global_load_dwordx4 v[116:119], v242, s[6:7]
	s_waitcnt lgkmcnt(4)
	v_mfma_f32_32x32x16_bf16 v[80:95], v[172:175], v[184:187], v[80:95]
	s_waitcnt lgkmcnt(2)
	v_mfma_f32_32x32x16_bf16 v[64:79], v[172:175], v[164:167], v[64:79]
	ds_read_b128 v[172:175], v150 offset:4096
	ds_read_b128 v[180:183], v150 offset:8192
	s_waitcnt vmcnt(13)
	ds_write_b128 v146, v[120:123] offset:49152
	global_load_dwordx4 v[120:123], v243, s[6:7]
	s_waitcnt lgkmcnt(2)
	v_mfma_f32_32x32x16_bf16 v[48:63], v[172:175], v[184:187], v[48:63]
	v_mfma_f32_32x32x16_bf16 v[32:47], v[172:175], v[164:167], v[32:47]
	s_waitcnt lgkmcnt(1)
	v_mfma_f32_32x32x16_bf16 v[16:31], v[180:183], v[184:187], v[16:31]
	v_mfma_f32_32x32x16_bf16 v[0:15], v[180:183], v[164:167], v[0:15]
	ds_read_b128 v[164:167], v152
	ds_read_b128 v[172:175], v152 offset:4096
	ds_read_b128 v[180:183], v188 offset:28672
	s_waitcnt lgkmcnt(0)
	s_barrier
;     template <int MT> __device__ __forceinline__ void run(const Params& P, f32x16 (&acc)[MT][2], int rbase, int pn, int wc, int lane) const {
;     ...
;             for (int rg = 0; rg < 16; ++rg) { const int r = ROWOF(rb, mt, rg);
;                 const float* x = (r < NPR ? P.xp + (size_t)r * 2048 : P.xs + (size_t)(r - NPR) * 2048) + c0;
;                 float* y = P.out + O_Y + (size_t)r * 2048 + c0;
;                 y[0] = ALPHA * x[0] + acc[mt][0][rg]; y[32] = ALPHA * x[32] + acc[mt][1][rg]; }
	v_mfma_f32_32x32x16_bf16 v[80:95], v[164:167], v[168:171], v[80:95]
	v_mfma_f32_32x32x16_bf16 v[64:79], v[164:167], v[180:183], v[64:79]
	v_mfma_f32_32x32x16_bf16 v[48:63], v[172:175], v[168:171], v[48:63]
	v_mfma_f32_32x32x16_bf16 v[32:47], v[172:175], v[180:183], v[32:47]
	ds_read_b128 v[164:167], v144 offset:57344
	ds_read_b128 v[172:175], v144 offset:61440
	ds_read_b128 v[184:187], v153 offset:8192
	ds_read_b128 v[188:191], v160
	v_mfma_f32_32x32x16_bf16 v[16:31], v[176:179], v[168:171], v[16:31]
	ds_read_b128 v[168:171], v126 offset:4096
	v_add_u32_e32 v240, s98, v124
	v_add_u32_e32 v241, 0x40000, v240
	v_add_u32_e32 v242, 0x80000, v240
	v_add_u32_e32 v243, 0xc0000, v240
	s_waitcnt vmcnt(13)
	ds_write_b128 v142, v[212:215]
	global_load_dwordx4 v[212:215], v240, s[4:5]
	v_mfma_f32_32x32x16_bf16 v[0:15], v[176:179], v[180:183], v[0:15]
	s_waitcnt lgkmcnt(2)
	v_mfma_f32_32x32x16_bf16 v[80:95], v[164:167], v[188:191], v[80:95]
	v_add_u32_e32 v180, v154, v147
	s_mov_b32 s15, s16
	s_waitcnt lgkmcnt(1)
	v_mfma_f32_32x32x16_bf16 v[64:79], v[164:167], v[168:171], v[64:79]
	s_waitcnt vmcnt(13)
	ds_write_b128 v142, v[216:219] offset:8192
	global_load_dwordx4 v[216:219], v241, s[4:5]
	v_mfma_f32_32x32x16_bf16 v[48:63], v[172:175], v[188:191], v[48:63]
	v_mfma_f32_32x32x16_bf16 v[32:47], v[172:175], v[168:171], v[32:47]
	s_waitcnt vmcnt(13)
	ds_write_b128 v142, v[220:223] offset:16384
	global_load_dwordx4 v[220:223], v242, s[4:5]
	v_mfma_f32_32x32x16_bf16 v[16:31], v[184:187], v[188:191], v[16:31]
	v_mfma_f32_32x32x16_bf16 v[0:15], v[184:187], v[168:171], v[0:15]
	ds_read_b128 v[164:167], v148 offset:57344
	ds_read_b128 v[168:171], v161
	ds_read_b128 v[172:175], v148 offset:61440
	ds_read_b128 v[176:179], v157 offset:8192
	ds_read_b128 v[180:183], v180 offset:4096
	ds_read_b128 v[184:187], v162
	s_waitcnt vmcnt(13)
	ds_write_b128 v142, v[224:227] offset:24576
	global_load_dwordx4 v[224:227], v240, s[6:7]
	s_waitcnt lgkmcnt(5)
	v_mfma_f32_32x32x16_bf16 v[80:95], v[164:167], v[168:171], v[80:95]
	s_waitcnt lgkmcnt(2)
	v_mfma_f32_32x32x16_bf16 v[64:79], v[164:167], v[180:183], v[64:79]
	s_waitcnt vmcnt(13)
	ds_write_b128 v142, v[228:231] offset:32768
	global_load_dwordx4 v[228:231], v241, s[6:7]
	v_mfma_f32_32x32x16_bf16 v[48:63], v[172:175], v[168:171], v[48:63]
	v_mfma_f32_32x32x16_bf16 v[32:47], v[172:175], v[180:183], v[32:47]
	ds_read_b128 v[164:167], v155 offset:8192
	ds_read_b128 v[172:175], v156 offset:8192
	s_waitcnt vmcnt(13)
	ds_write_b128 v142, v[232:235] offset:40960
	global_load_dwordx4 v[232:235], v242, s[6:7]
	s_waitcnt lgkmcnt(2)
	v_mfma_f32_32x32x16_bf16 v[16:31], v[164:167], v[168:171], v[16:31]
	v_mfma_f32_32x32x16_bf16 v[0:15], v[164:167], v[180:183], v[0:15]
	ds_read_b128 v[164:167], v150 offset:57344
	ds_read_b128 v[168:171], v150 offset:61440
	v_add_u32_e32 v180, v154, v149
	ds_read_b128 v[180:183], v180 offset:4096
	ds_read_b128 v[188:191], v163
	s_waitcnt vmcnt(13)
	ds_write_b128 v142, v[236:239] offset:49152
	global_load_dwordx4 v[236:239], v243, s[6:7]
	s_waitcnt lgkmcnt(4)
	v_mfma_f32_32x32x16_bf16 v[80:95], v[164:167], v[184:187], v[80:95]
	s_waitcnt lgkmcnt(2)
	v_mfma_f32_32x32x16_bf16 v[64:79], v[164:167], v[180:183], v[64:79]
	v_mfma_f32_32x32x16_bf16 v[48:63], v[168:171], v[184:187], v[48:63]
	v_mfma_f32_32x32x16_bf16 v[32:47], v[168:171], v[180:183], v[32:47]
	ds_read_b128 v[164:167], v152 offset:57344
	ds_read_b128 v[168:171], v152 offset:61440
	v_mfma_f32_32x32x16_bf16 v[16:31], v[172:175], v[184:187], v[16:31]
	v_mfma_f32_32x32x16_bf16 v[0:15], v[172:175], v[180:183], v[0:15]
	v_add_u32_e32 v172, v154, v151
	ds_read_b128 v[172:175], v172 offset:4096
	s_waitcnt lgkmcnt(0)
	s_barrier
	v_mfma_f32_32x32x16_bf16 v[80:95], v[164:167], v[188:191], v[80:95]
	v_mfma_f32_32x32x16_bf16 v[64:79], v[164:167], v[172:175], v[64:79]
	v_mfma_f32_32x32x16_bf16 v[48:63], v[168:171], v[188:191], v[48:63]
	v_mfma_f32_32x32x16_bf16 v[32:47], v[168:171], v[172:175], v[32:47]
	v_mfma_f32_32x32x16_bf16 v[16:31], v[176:179], v[188:191], v[16:31]
	v_mfma_f32_32x32x16_bf16 v[0:15], v[176:179], v[172:175], v[0:15]
	s_cmp_lt_u32 s15, 32
	s_cbranch_scc1 .LBB0_2403
	s_mulk_i32 s14, 0xc0
	s_waitcnt vmcnt(0)
	v_add_u32_e32 v96, s14, v158
	v_cmp_lt_i32_e32 vcc, s11, v96
	s_and_saveexec_b64 s[4:5], vcc
	s_xor_b64 s[4:5], exec, s[4:5]
	s_cbranch_execz .LBB0_2406
	v_add_u32_e32 v126, 0xffffc000, v96
	v_lshlrev_b64 v[98:99], 13, v[126:127]
	v_mov_b32_e32 v97, v127
	s_waitcnt vmcnt(4)
	v_lshl_add_u64 v[100:101], s[66:67], 0, v[98:99]
	v_lshlrev_b64 v[102:103], 13, v[96:97]

; #define G_STORE(BUF) do { char* l_ = lds + (BUF) * STAGE + wofs; \
;         *(uint4*)(l_) = ra0; *(uint4*)(l_ + 8192) = ra1; *(uint4*)(l_ + 16384) = ra2; if (MT == 4) *(uint4*)(l_ + 24576) = ra3; \
;         *(uint4*)(l_ + ABYTES) = rb0; *(uint4*)(l_ + ABYTES + 8192) = rb1; *(uint4*)(l_ + ABYTES + 16384) = rb2; *(uint4*)(l_ + ABYTES + 24576) = rb3; } while (0)
; template <int MT, bool PIN, class Epi>
; __device__ __forceinline__ void gemm_phase(const Params& P, const bf16_t* __restrict__ A, const bf16_t* __restrict__ Bt, int nM, int nN, int K, const Epi epi, char* lds) {
;     ...
;         const long L = (long)it * G + blockIdx.x; if (L >= nT) break;
;         int pm, pn; map_tile((int)L, nM, nN, pm, pn);
;         const char* Ab = (const char*)(A + (size_t)pm * BM * K);
;         const char* Bb = (const char*)(Bt + (size_t)pn * 256 * K);
;         const unsigned toff = (unsigned)(srow * K + sch * 8) * 2u, rs = (unsigned)K * 128u;
;         uint4 ra0, ra1, ra2, ra3, rb0, rb1, rb2, rb3;
;     ...
;         G_LOAD(0);
;         f32x16 acc[MT][2];
; #pragma unroll
;         for (int a = 0; a < MT; ++a)
; #pragma unroll
;             for (int b = 0; b < 2; ++b)
; #pragma unroll
;                 for (int e = 0; e < 16; ++e) acc[a][b][e] = 0.f;
;         bf16x8 fa[2][MT], fb[2][2];
;         __syncthreads();
;         G_STORE(0);
;         G_LOAD(1);
;         __syncthreads();
.LBB0_2779:
	s_mul_i32 s10, s14, s33
	s_mul_hi_u32 s11, s14, s84
	s_add_i32 s11, s11, s10
	s_mul_i32 s10, s14, s84
	s_add_u32 s10, s10, s2
	s_addc_u32 s11, s11, 0
	v_cmp_gt_i64_e32 vcc, s[10:11], v[140:141]
	s_mov_b64 s[12:13], -1
	s_cbranch_vccnz .LBB0_2778
	s_and_b32 s11, s10, 7
	s_mulk_i32 s11, 0x58
	s_ashr_i32 s10, s10, 3
	s_add_i32 s10, s11, s10
	s_ashr_i32 s11, s10, 31
	s_lshr_b32 s11, s11, 26
	s_add_i32 s11, s10, s11
	s_ashr_i32 s12, s11, 6
	s_lshl_b32 s12, s12, 3
	s_sub_i32 s13, 0x58, s12
	s_min_i32 s13, s13, 8
	s_abs_i32 s17, s13
	v_cvt_f32_u32_e32 v0, s17
	s_sub_i32 s19, 0, s17
	s_andn2_b32 s11, s11, 63
	s_sub_i32 s10, s10, s11
	v_rcp_iflag_f32_e32 v0, v0
	s_abs_i32 s11, s10
	s_xor_b32 s18, s10, s13
	s_ashr_i32 s18, s18, 31
	v_mul_f32_e32 v0, 0x4f7ffffe, v0
	v_cvt_u32_f32_e32 v0, v0
	s_nop 0
	v_readfirstlane_b32 s20, v0
	s_mul_i32 s19, s19, s20
	s_mul_hi_u32 s19, s20, s19
	s_add_i32 s20, s20, s19
	s_mul_hi_u32 s19, s11, s20
	s_mul_i32 s20, s19, s17
	s_sub_i32 s11, s11, s20
	s_add_i32 s21, s19, 1
	s_sub_i32 s20, s11, s17
	s_cmp_ge_u32 s11, s17
	s_cselect_b32 s19, s21, s19
	s_cselect_b32 s11, s20, s11
	s_add_i32 s20, s19, 1
	s_cmp_ge_u32 s11, s17
	s_cselect_b32 s11, s20, s19
	s_xor_b32 s11, s11, s18
	s_sub_i32 s17, s11, s18
	s_mul_i32 s11, s17, s13
	s_sub_i32 s18, s10, s11
	s_add_i32 s18, s18, s12
	s_mul_i32 s10, s18, 0x210000
	s_mul_hi_i32 s11, s18, 0x210000
	s_add_u32 s10, s48, s10
	s_addc_u32 s11, s49, s11
	s_mul_i32 s12, s17, 0x2c0000
	s_mul_hi_i32 s13, s17, 0x2c0000
	s_add_u32 s12, s1, s12
	v_lshl_add_u64 v[28:29], s[10:11], 0, v[126:127]
	v_lshl_add_u64 v[0:1], s[10:11], 0, v[128:129]
	s_addc_u32 s13, s3, s13
	global_load_dwordx4 v[38:41], v[28:29], off
	global_load_dwordx4 v[42:45], v[0:1], off
	v_lshl_add_u64 v[0:1], s[10:11], 0, v[130:131]
	v_lshl_add_u64 v[30:31], s[12:13], 0, v[126:127]
	global_load_dwordx4 v[46:49], v[0:1], off
	global_load_dwordx4 v[50:53], v[30:31], off
	v_lshl_add_u64 v[0:1], s[12:13], 0, v[128:129]
	v_lshl_add_u64 v[2:3], s[12:13], 0, v[130:131]
	global_load_dwordx4 v[54:57], v[0:1], off
	global_load_dwordx4 v[58:61], v[2:3], off
	v_lshl_add_u64 v[0:1], s[12:13], 0, v[132:133]
	v_lshl_add_u64 v[32:33], s[10:11], 0, v[134:135]
	global_load_dwordx4 v[62:65], v[0:1], off
	v_lshl_add_u64 v[34:35], s[10:11], 0, v[136:137]
	v_lshl_add_u64 v[36:37], s[12:13], 0, v[134:135]
	v_lshl_add_u64 v[66:67], s[12:13], 0, v[136:137]
	v_lshl_add_u64 v[68:69], s[12:13], 0, v[138:139]
	s_barrier
	global_load_dwordx4 v[96:99], v[28:29], off offset:128
	global_load_dwordx4 v[100:103], v[32:33], off
	global_load_dwordx4 v[108:111], v[34:35], off
	global_load_dwordx4 v[104:107], v[30:31], off offset:128
	global_load_dwordx4 v[112:115], v[36:37], off
	global_load_dwordx4 v[116:119], v[66:67], off
	global_load_dwordx4 v[120:123], v[68:69], off
	global_load_dwordx4 v[212:215], v[28:29], off offset:256
	global_load_dwordx4 v[216:219], v[32:33], off offset:128
	global_load_dwordx4 v[220:223], v[34:35], off offset:128
	global_load_dwordx4 v[224:227], v[30:31], off offset:256
	global_load_dwordx4 v[228:231], v[36:37], off offset:128
	global_load_dwordx4 v[232:235], v[66:67], off offset:128
	global_load_dwordx4 v[236:239], v[68:69], off offset:128
	v_mov_b32_e32 v0, 0
	s_mov_b32 s20, 0
	s_movk_i32 s19, 0x180
	v_mov_b32_e32 v1, v0
	v_mov_b32_e32 v2, v0
	v_mov_b32_e32 v3, v0
	v_mov_b32_e32 v4, v0
	v_mov_b32_e32 v5, v0
	v_mov_b32_e32 v6, v0
	v_mov_b32_e32 v7, v0
	v_mov_b32_e32 v8, v0
	v_mov_b32_e32 v9, v0
	v_mov_b32_e32 v10, v0
	v_mov_b32_e32 v11, v0
	v_mov_b32_e32 v12, v0
	v_mov_b32_e32 v13, v0
	v_mov_b32_e32 v14, v0
	v_mov_b32_e32 v15, v0
	v_mov_b32_e32 v16, v0
	v_mov_b32_e32 v17, v0
	v_mov_b32_e32 v18, v0
	v_mov_b32_e32 v19, v0
	v_mov_b32_e32 v20, v0
	v_mov_b32_e32 v21, v0
	v_mov_b32_e32 v22, v0
	v_mov_b32_e32 v23, v0
	v_mov_b32_e32 v24, v0
	v_mov_b32_e32 v25, v0
	v_mov_b32_e32 v26, v0
	v_mov_b32_e32 v27, v0
	v_mov_b32_e32 v28, v0
	v_mov_b32_e32 v29, v0
	v_mov_b32_e32 v30, v0
	v_mov_b32_e32 v31, v0
	v_mov_b32_e32 v32, v0
	v_mov_b32_e32 v33, v0
	v_mov_b32_e32 v34, v0
	v_mov_b32_e32 v35, v0
	v_mov_b32_e32 v36, v0
	v_mov_b32_e32 v37, v0
	v_mov_b32_e32 v66, v0
	v_mov_b32_e32 v67, v0
	v_mov_b32_e32 v68, v0
	v_mov_b32_e32 v69, v0
	v_mov_b32_e32 v70, v0
	v_mov_b32_e32 v71, v0
	v_mov_b32_e32 v72, v0
	v_mov_b32_e32 v73, v0
	v_mov_b32_e32 v74, v0
	v_mov_b32_e32 v75, v0
	v_mov_b32_e32 v76, v0
	v_mov_b32_e32 v77, v0
	v_mov_b32_e32 v78, v0
	v_mov_b32_e32 v79, v0
	v_mov_b32_e32 v80, v0
	s_waitcnt vmcnt(20)
	ds_write_b128 v142, v[38:41]
	s_waitcnt vmcnt(19)
	ds_write_b128 v142, v[42:45] offset:8192
	s_waitcnt vmcnt(18)
	ds_write_b128 v142, v[46:49] offset:16384
	s_waitcnt vmcnt(17)
	ds_write_b128 v142, v[50:53] offset:24576
	s_waitcnt vmcnt(16)
	ds_write_b128 v142, v[54:57] offset:32768
	s_waitcnt vmcnt(15)
	ds_write_b128 v142, v[58:61] offset:40960
	s_waitcnt vmcnt(14)
	ds_write_b128 v142, v[62:65] offset:49152
	v_mov_b32_e32 v38, v0
	v_mov_b32_e32 v39, v0
	v_mov_b32_e32 v40, v0
	v_mov_b32_e32 v41, v0
	v_mov_b32_e32 v42, v0
	v_mov_b32_e32 v43, v0
	v_mov_b32_e32 v44, v0
	v_mov_b32_e32 v45, v0
	v_mov_b32_e32 v46, v0
	v_mov_b32_e32 v47, v0
	v_mov_b32_e32 v48, v0
	v_mov_b32_e32 v49, v0
	v_mov_b32_e32 v50, v0
	v_mov_b32_e32 v51, v0
	v_mov_b32_e32 v52, v0
	v_mov_b32_e32 v53, v0
	v_mov_b32_e32 v54, v0
	v_mov_b32_e32 v55, v0
	v_mov_b32_e32 v56, v0
	v_mov_b32_e32 v57, v0
	v_mov_b32_e32 v58, v0
	v_mov_b32_e32 v59, v0
	v_mov_b32_e32 v60, v0
	v_mov_b32_e32 v61, v0
	v_mov_b32_e32 v62, v0
	v_mov_b32_e32 v63, v0
	v_mov_b32_e32 v64, v0
	v_mov_b32_e32 v65, v0
	v_mov_b32_e32 v81, v0
	v_mov_b32_e32 v82, v0
	v_mov_b32_e32 v83, v0
	v_mov_b32_e32 v84, v0
	v_mov_b32_e32 v85, v0
	v_mov_b32_e32 v86, v0
	v_mov_b32_e32 v87, v0
	v_mov_b32_e32 v88, v0
	v_mov_b32_e32 v89, v0
	v_mov_b32_e32 v90, v0
	v_mov_b32_e32 v91, v0
	v_mov_b32_e32 v92, v0
	v_mov_b32_e32 v93, v0
	v_mov_b32_e32 v94, v0
	v_mov_b32_e32 v95, v0
	s_waitcnt lgkmcnt(0)
	s_barrier
.LBB0_2781:
	v_add_u32_e32 v182, v146, v143
	ds_read_b128 v[166:169], v145
	ds_read_b128 v[170:173], v145 offset:4096
	ds_read_b128 v[174:177], v145 offset:8192
	ds_read_b128 v[178:181], v182 offset:24576
	ds_read_b128 v[182:185], v182 offset:28672
	s_add_i32 s21, s20, 2
	s_min_u32 s22, s19, 0x2b80
	s_add_i32 s98, s19, 0x80
	s_min_u32 s98, s98, 0x2b80
	s_addk_i32 s19, 0x100
	v_add_u32_e32 v240, s22, v126
	v_add_u32_e32 v241, 0xb0000, v240
	v_add_u32_e32 v242, 0x160000, v240
	v_add_u32_e32 v243, 0x210000, v240
	s_waitcnt lgkmcnt(1)
	v_mfma_f32_32x32x16_bf16 v[80:95], v[166:169], v[178:181], v[80:95]
	v_add_u32_e32 v190, v146, v150
	v_add_u32_e32 v198, v155, v143
	s_waitcnt lgkmcnt(0)
	v_mfma_f32_32x32x16_bf16 v[64:79], v[166:169], v[182:185], v[64:79]
	ds_read_b128 v[166:169], v149
	s_waitcnt vmcnt(13)
	ds_write_b128 v142, v[96:99] offset:57344
	global_load_dwordx4 v[96:99], v240, s[10:11]
	v_mfma_f32_32x32x16_bf16 v[48:63], v[170:173], v[178:181], v[48:63]
	v_mfma_f32_32x32x16_bf16 v[32:47], v[170:173], v[182:185], v[32:47]
	s_waitcnt vmcnt(13)
	ds_write_b128 v147, v[100:103] offset:8192
	global_load_dwordx4 v[100:103], v241, s[10:11]
	v_mfma_f32_32x32x16_bf16 v[0:15], v[174:177], v[182:185], v[0:15]
	v_add_u32_e32 v182, v146, v148
	v_mfma_f32_32x32x16_bf16 v[16:31], v[174:177], v[178:181], v[16:31]
	ds_read_b128 v[170:173], v182 offset:24576
	ds_read_b128 v[174:177], v149 offset:4096
	ds_read_b128 v[178:181], v153 offset:8192
	ds_read_b128 v[182:185], v182 offset:28672
	ds_read_b128 v[186:189], v190 offset:24576
	s_waitcnt vmcnt(13)
	ds_write_b128 v147, v[108:111] offset:16384
	global_load_dwordx4 v[108:111], v242, s[10:11]
	s_waitcnt lgkmcnt(5)
	v_mfma_f32_32x32x16_bf16 v[80:95], v[166:169], v[170:173], v[80:95]
	s_waitcnt lgkmcnt(2)
	v_mfma_f32_32x32x16_bf16 v[64:79], v[166:169], v[182:185], v[64:79]
	s_waitcnt vmcnt(13)
	ds_write_b128 v147, v[104:107] offset:24576
	global_load_dwordx4 v[104:107], v240, s[12:13]
	v_mfma_f32_32x32x16_bf16 v[48:63], v[174:177], v[170:173], v[48:63]
	v_mfma_f32_32x32x16_bf16 v[32:47], v[174:177], v[182:185], v[32:47]
	ds_read_b128 v[166:169], v149 offset:8192
	ds_read_b128 v[174:177], v151
	s_waitcnt vmcnt(13)
	ds_write_b128 v147, v[112:115] offset:32768
	global_load_dwordx4 v[112:115], v241, s[12:13]
	s_waitcnt lgkmcnt(2)
	v_mfma_f32_32x32x16_bf16 v[16:31], v[166:169], v[170:173], v[16:31]
	v_mfma_f32_32x32x16_bf16 v[0:15], v[166:169], v[182:185], v[0:15]
	ds_read_b128 v[166:169], v190 offset:28672
	v_add_u32_e32 v190, v146, v152
	ds_read_b128 v[170:173], v190 offset:24576
	s_waitcnt vmcnt(13)
	ds_write_b128 v147, v[116:119] offset:40960
	global_load_dwordx4 v[116:119], v242, s[12:13]
	s_waitcnt lgkmcnt(4)
	v_mfma_f32_32x32x16_bf16 v[80:95], v[174:177], v[186:189], v[80:95]
	s_waitcnt lgkmcnt(2)
	v_mfma_f32_32x32x16_bf16 v[64:79], v[174:177], v[166:169], v[64:79]
	ds_read_b128 v[174:177], v151 offset:4096
	ds_read_b128 v[182:185], v151 offset:8192
	s_waitcnt vmcnt(13)
	ds_write_b128 v147, v[120:123] offset:49152
	global_load_dwordx4 v[120:123], v243, s[12:13]
	s_waitcnt lgkmcnt(2)
	v_mfma_f32_32x32x16_bf16 v[48:63], v[174:177], v[186:189], v[48:63]
	v_mfma_f32_32x32x16_bf16 v[32:47], v[174:177], v[166:169], v[32:47]
	s_waitcnt lgkmcnt(1)
	v_mfma_f32_32x32x16_bf16 v[16:31], v[182:185], v[186:189], v[16:31]
	v_mfma_f32_32x32x16_bf16 v[0:15], v[182:185], v[166:169], v[0:15]
	ds_read_b128 v[166:169], v153
	ds_read_b128 v[174:177], v153 offset:4096
	ds_read_b128 v[182:185], v190 offset:28672
	s_waitcnt lgkmcnt(0)
	s_barrier
	v_mfma_f32_32x32x16_bf16 v[80:95], v[166:169], v[170:173], v[80:95]
	v_mfma_f32_32x32x16_bf16 v[64:79], v[166:169], v[182:185], v[64:79]
	v_mfma_f32_32x32x16_bf16 v[48:63], v[174:177], v[170:173], v[48:63]
	v_mfma_f32_32x32x16_bf16 v[32:47], v[174:177], v[182:185], v[32:47]
	ds_read_b128 v[166:169], v145 offset:57344
	ds_read_b128 v[174:177], v145 offset:61440
	ds_read_b128 v[186:189], v154 offset:8192
	ds_read_b128 v[190:193], v161
	v_mfma_f32_32x32x16_bf16 v[16:31], v[178:181], v[170:173], v[16:31]
	ds_read_b128 v[170:173], v198 offset:4096
	v_add_u32_e32 v240, s98, v126
	v_add_u32_e32 v241, 0xb0000, v240
	v_add_u32_e32 v242, 0x160000, v240
	v_add_u32_e32 v243, 0x210000, v240
	s_waitcnt vmcnt(13)
	ds_write_b128 v142, v[212:215]
	global_load_dwordx4 v[212:215], v240, s[10:11]
	v_mfma_f32_32x32x16_bf16 v[0:15], v[178:181], v[182:185], v[0:15]
	s_waitcnt lgkmcnt(2)
	v_mfma_f32_32x32x16_bf16 v[80:95], v[166:169], v[190:193], v[80:95]
	v_add_u32_e32 v182, v155, v148
	s_mov_b32 s20, s21
	s_waitcnt lgkmcnt(1)
	v_mfma_f32_32x32x16_bf16 v[64:79], v[166:169], v[170:173], v[64:79]
	s_waitcnt vmcnt(13)
	ds_write_b128 v142, v[216:219] offset:8192
	global_load_dwordx4 v[216:219], v241, s[10:11]
	v_mfma_f32_32x32x16_bf16 v[48:63], v[174:177], v[190:193], v[48:63]
	v_mfma_f32_32x32x16_bf16 v[32:47], v[174:177], v[170:173], v[32:47]
	s_waitcnt vmcnt(13)
	ds_write_b128 v142, v[220:223] offset:16384
	global_load_dwordx4 v[220:223], v242, s[10:11]
	v_mfma_f32_32x32x16_bf16 v[16:31], v[186:189], v[190:193], v[16:31]
	v_mfma_f32_32x32x16_bf16 v[0:15], v[186:189], v[170:173], v[0:15]
	ds_read_b128 v[166:169], v149 offset:57344
	ds_read_b128 v[170:173], v162
	ds_read_b128 v[174:177], v149 offset:61440
	ds_read_b128 v[178:181], v158 offset:8192
	ds_read_b128 v[182:185], v182 offset:4096
	ds_read_b128 v[186:189], v163
	s_waitcnt vmcnt(13)
	ds_write_b128 v142, v[224:227] offset:24576
	global_load_dwordx4 v[224:227], v240, s[12:13]
	s_waitcnt lgkmcnt(5)
	v_mfma_f32_32x32x16_bf16 v[80:95], v[166:169], v[170:173], v[80:95]
	s_waitcnt lgkmcnt(2)
	v_mfma_f32_32x32x16_bf16 v[64:79], v[166:169], v[182:185], v[64:79]
	s_waitcnt vmcnt(13)
;     template <int MT> __device__ __forceinline__ void run(const Params& P, f32x16 (&acc)[MT][2], int rbase, int pn, int wc, int lane) const {
;     ...
;             for (int rg = 0; rg < 16; ++rg) { const int r = ROWOF(rb, mt, rg);
;                 float* y = P.out + O_Y + (size_t)r * 2048 + c0;
;                 y[0] = ALPHA * y[0] + acc[mt][0][rg]; y[32] = ALPHA * y[32] + acc[mt][1][rg]; }
	ds_write_b128 v142, v[228:231] offset:32768
	global_load_dwordx4 v[228:231], v241, s[12:13]
	v_mfma_f32_32x32x16_bf16 v[48:63], v[174:177], v[170:173], v[48:63]
	v_mfma_f32_32x32x16_bf16 v[32:47], v[174:177], v[182:185], v[32:47]
	ds_read_b128 v[166:169], v156 offset:8192
	ds_read_b128 v[174:177], v157 offset:8192
	s_waitcnt vmcnt(13)
	ds_write_b128 v142, v[232:235] offset:40960
	global_load_dwordx4 v[232:235], v242, s[12:13]
	s_waitcnt lgkmcnt(2)
	v_mfma_f32_32x32x16_bf16 v[16:31], v[166:169], v[170:173], v[16:31]
	v_mfma_f32_32x32x16_bf16 v[0:15], v[166:169], v[182:185], v[0:15]
	ds_read_b128 v[166:169], v151 offset:57344
	ds_read_b128 v[170:173], v151 offset:61440
	v_add_u32_e32 v182, v155, v150
	ds_read_b128 v[182:185], v182 offset:4096
	ds_read_b128 v[190:193], v164
	s_waitcnt vmcnt(13)
	ds_write_b128 v142, v[236:239] offset:49152
	global_load_dwordx4 v[236:239], v243, s[12:13]
	s_waitcnt lgkmcnt(4)
	v_mfma_f32_32x32x16_bf16 v[80:95], v[166:169], v[186:189], v[80:95]
	s_waitcnt lgkmcnt(2)
	v_mfma_f32_32x32x16_bf16 v[64:79], v[166:169], v[182:185], v[64:79]
	v_mfma_f32_32x32x16_bf16 v[48:63], v[170:173], v[186:189], v[48:63]
	v_mfma_f32_32x32x16_bf16 v[32:47], v[170:173], v[182:185], v[32:47]
	ds_read_b128 v[166:169], v153 offset:57344
	ds_read_b128 v[170:173], v153 offset:61440
	v_mfma_f32_32x32x16_bf16 v[16:31], v[174:177], v[186:189], v[16:31]
	v_mfma_f32_32x32x16_bf16 v[0:15], v[174:177], v[182:185], v[0:15]
	v_add_u32_e32 v174, v155, v152
	ds_read_b128 v[174:177], v174 offset:4096
	s_waitcnt lgkmcnt(0)
	s_barrier
	v_mfma_f32_32x32x16_bf16 v[80:95], v[166:169], v[190:193], v[80:95]
	v_mfma_f32_32x32x16_bf16 v[64:79], v[166:169], v[174:177], v[64:79]
	v_mfma_f32_32x32x16_bf16 v[48:63], v[170:173], v[190:193], v[48:63]
	v_mfma_f32_32x32x16_bf16 v[32:47], v[170:173], v[174:177], v[32:47]
	v_mfma_f32_32x32x16_bf16 v[16:31], v[178:181], v[190:193], v[16:31]
	v_mfma_f32_32x32x16_bf16 v[0:15], v[178:181], v[174:177], v[0:15]
	s_cmp_lt_u32 s20, 88
	s_cbranch_scc1 .LBB0_2781
	s_mulk_i32 s18, 0xc0
	s_waitcnt vmcnt(0)
	v_add_u32_e32 v98, s18, v159
	v_lshl_or_b32 v96, s17, 8, v160
	v_ashrrev_i32_e32 v97, 31, v96
	v_ashrrev_i32_e32 v99, 31, v98
	s_waitcnt vmcnt(4)
	v_or_b32_e32 v102, 1, v98
	v_or_b32_e32 v104, 2, v98
	v_or_b32_e32 v106, 3, v98
	v_lshl_add_u64 v[96:97], v[96:97], 2, s[88:89]
	v_lshlrev_b64 v[100:101], 13, v[98:99]
	v_ashrrev_i32_e32 v103, 31, v102
	v_ashrrev_i32_e32 v105, 31, v104
	v_ashrrev_i32_e32 v107, 31, v106
	v_lshl_add_u64 v[100:101], v[96:97], 0, v[100:101]
	v_lshlrev_b64 v[102:103], 13, v[102:103]
	v_lshlrev_b64 v[104:105], 13, v[104:105]
	v_lshlrev_b64 v[106:107], 13, v[106:107]
	v_lshl_add_u64 v[102:103], v[96:97], 0, v[102:103]
	v_lshl_add_u64 v[104:105], v[96:97], 0, v[104:105]
	v_lshl_add_u64 v[106:107], v[96:97], 0, v[106:107]
	global_load_dword v99, v[100:101], off
	global_load_dword v165, v[100:101], off offset:128
	global_load_dword v166, v[102:103], off
	global_load_dword v167, v[102:103], off offset:128
	global_load_dword v168, v[104:105], off
	global_load_dword v169, v[104:105], off offset:128
	global_load_dword v170, v[106:107], off
	global_load_dword v171, v[106:107], off offset:128
	s_waitcnt vmcnt(10)
	v_or_b32_e32 v108, 8, v98
	v_ashrrev_i32_e32 v109, 31, v108
	v_or_b32_e32 v110, 9, v98
	v_or_b32_e32 v112, 10, v98
	v_or_b32_e32 v114, 11, v98
	v_lshlrev_b64 v[108:109], 13, v[108:109]
	v_ashrrev_i32_e32 v111, 31, v110
	v_ashrrev_i32_e32 v113, 31, v112
	v_ashrrev_i32_e32 v115, 31, v114
	v_lshl_add_u64 v[108:109], v[96:97], 0, v[108:109]
	v_lshlrev_b64 v[110:111], 13, v[110:111]
	v_lshlrev_b64 v[112:113], 13, v[112:113]
	v_lshlrev_b64 v[114:115], 13, v[114:115]
	v_lshl_add_u64 v[110:111], v[96:97], 0, v[110:111]
	v_lshl_add_u64 v[112:113], v[96:97], 0, v[112:113]
	v_lshl_add_u64 v[114:115], v[96:97], 0, v[114:115]
	global_load_dword v172, v[108:109], off
	global_load_dword v173, v[108:109], off offset:128
	global_load_dword v174, v[110:111], off
	global_load_dword v175, v[110:111], off offset:128
	global_load_dword v176, v[112:113], off
	global_load_dword v177, v[112:113], off offset:128
	global_load_dword v178, v[114:115], off
	global_load_dword v179, v[114:115], off offset:128
	s_waitcnt vmcnt(17)
	v_or_b32_e32 v116, 16, v98
	v_ashrrev_i32_e32 v117, 31, v116
	v_lshlrev_b64 v[116:117], 13, v[116:117]
	v_lshl_add_u64 v[116:117], v[96:97], 0, v[116:117]
	global_load_dword v180, v[116:117], off
	global_load_dword v181, v[116:117], off offset:128
	v_or_b32_e32 v118, 17, v98
	v_ashrrev_i32_e32 v119, 31, v118
	s_waitcnt vmcnt(18)
	v_or_b32_e32 v120, 18, v98
	v_lshlrev_b64 v[118:119], 13, v[118:119]
	v_ashrrev_i32_e32 v121, 31, v120
	v_or_b32_e32 v122, 19, v98
	v_lshl_add_u64 v[118:119], v[96:97], 0, v[118:119]
	v_lshlrev_b64 v[120:121], 13, v[120:121]
	v_ashrrev_i32_e32 v123, 31, v122
	v_lshl_add_u64 v[120:121], v[96:97], 0, v[120:121]
	global_load_dword v182, v[118:119], off
	global_load_dword v183, v[118:119], off offset:128
	global_load_dword v184, v[120:121], off
	global_load_dword v185, v[120:121], off offset:128
	v_lshlrev_b64 v[122:123], 13, v[122:123]
	v_lshl_add_u64 v[122:123], v[96:97], 0, v[122:123]
	global_load_dword v186, v[122:123], off
	global_load_dword v187, v[122:123], off offset:128
	s_add_i32 s14, s14, 1
	s_mov_b64 s[12:13], 0
	s_waitcnt vmcnt(23)
	v_fmamk_f32 v80, v99, 0x3f9837f0, v80
	s_waitcnt vmcnt(22)
	v_fmamk_f32 v64, v165, 0x3f9837f0, v64
	global_store_dword v[100:101], v80, off
	global_store_dword v[100:101], v64, off offset:128
	s_waitcnt vmcnt(23)
	v_fmamk_f32 v64, v166, 0x3f9837f0, v81
	s_waitcnt vmcnt(22)
	v_fmamk_f32 v65, v167, 0x3f9837f0, v65
	s_waitcnt vmcnt(21)
;     template <int MT> __device__ __forceinline__ void run(const Params& P, f32x16 (&acc)[MT][2], int rbase, int pn, int wc, int lane) const {
;     ...
;         for (int mt = 0; mt < MT; ++mt)
; #pragma unroll
;             for (int rg = 0; rg < 16; ++rg) { const int r = ROWOF(rb, mt, rg);
;                 float* y = P.out + O_Y + (size_t)r * 2048 + c0;
;                 y[0] = ALPHA * y[0] + acc[mt][0][rg]; y[32] = ALPHA * y[32] + acc[mt][1][rg]; }
	v_fmamk_f32 v80, v168, 0x3f9837f0, v82
	s_waitcnt vmcnt(20)
	v_fmamk_f32 v66, v169, 0x3f9837f0, v66
	global_store_dword v[102:103], v64, off
	global_store_dword v[102:103], v65, off offset:128
	global_store_dword v[104:105], v80, off
	global_store_dword v[104:105], v66, off offset:128
	s_waitcnt vmcnt(23)
	v_fmamk_f32 v64, v170, 0x3f9837f0, v83
	global_store_dword v[106:107], v64, off
	s_waitcnt vmcnt(23)
	v_fmamk_f32 v64, v171, 0x3f9837f0, v67
	global_store_dword v[106:107], v64, off offset:128
	v_or_b32_e32 v66, 25, v98
	v_ashrrev_i32_e32 v67, 31, v66
	v_lshlrev_b64 v[66:67], 13, v[66:67]
	v_lshl_add_u64 v[66:67], v[96:97], 0, v[66:67]
	s_waitcnt vmcnt(23)
	v_fmamk_f32 v64, v172, 0x3f9837f0, v84
	global_store_dword v[108:109], v64, off
	s_waitcnt vmcnt(23)
	v_fmamk_f32 v64, v173, 0x3f9837f0, v68
	global_store_dword v[108:109], v64, off offset:128
	s_waitcnt vmcnt(23)
	v_fmamk_f32 v64, v174, 0x3f9837f0, v85
	global_store_dword v[110:111], v64, off
	s_waitcnt vmcnt(23)
	v_fmamk_f32 v64, v175, 0x3f9837f0, v69
	global_store_dword v[110:111], v64, off offset:128
	s_waitcnt vmcnt(23)
	v_fmamk_f32 v64, v176, 0x3f9837f0, v86
	global_store_dword v[112:113], v64, off
	s_waitcnt vmcnt(23)
	v_fmamk_f32 v64, v177, 0x3f9837f0, v70
	global_store_dword v[112:113], v64, off offset:128
	s_waitcnt vmcnt(23)
	v_fmamk_f32 v64, v178, 0x3f9837f0, v87
	v_add_u32_e32 v70, 33, v98
	global_store_dword v[114:115], v64, off
	s_waitcnt vmcnt(23)
	v_fmamk_f32 v64, v179, 0x3f9837f0, v71
	v_ashrrev_i32_e32 v71, 31, v70
	v_lshlrev_b64 v[70:71], 13, v[70:71]
	v_lshl_add_u64 v[80:81], v[96:97], 0, v[70:71]
	v_add_u32_e32 v70, 34, v98
	v_ashrrev_i32_e32 v71, 31, v70
	v_lshlrev_b64 v[70:71], 13, v[70:71]
	v_lshl_add_u64 v[82:83], v[96:97], 0, v[70:71]
	v_add_u32_e32 v70, 35, v98
	global_store_dword v[114:115], v64, off offset:128
	s_waitcnt vmcnt(23)
	v_fmamk_f32 v64, v180, 0x3f9837f0, v88
	v_ashrrev_i32_e32 v71, 31, v70
	global_store_dword v[116:117], v64, off
	s_waitcnt vmcnt(23)
	v_fmamk_f32 v64, v181, 0x3f9837f0, v72
	v_lshlrev_b64 v[70:71], 13, v[70:71]
	global_store_dword v[116:117], v64, off offset:128
	s_waitcnt vmcnt(23)
	v_fmamk_f32 v64, v182, 0x3f9837f0, v89
	v_lshl_add_u64 v[84:85], v[96:97], 0, v[70:71]
	v_add_u32_e32 v70, 40, v98
	global_store_dword v[118:119], v64, off
	s_waitcnt vmcnt(23)
	v_fmamk_f32 v64, v183, 0x3f9837f0, v73
	v_ashrrev_i32_e32 v71, 31, v70
	global_store_dword v[118:119], v64, off offset:128
	s_waitcnt vmcnt(23)
	v_fmamk_f32 v64, v184, 0x3f9837f0, v90
	v_lshlrev_b64 v[70:71], 13, v[70:71]
	global_store_dword v[120:121], v64, off
	s_waitcnt vmcnt(23)
	v_fmamk_f32 v64, v185, 0x3f9837f0, v74
	v_lshl_add_u64 v[86:87], v[96:97], 0, v[70:71]
	v_add_u32_e32 v70, 41, v98
	global_store_dword v[120:121], v64, off offset:128
	s_waitcnt vmcnt(23)
	v_fmamk_f32 v64, v186, 0x3f9837f0, v91
	v_ashrrev_i32_e32 v71, 31, v70
	global_store_dword v[122:123], v64, off
	s_waitcnt vmcnt(23)
	v_fmamk_f32 v64, v187, 0x3f9837f0, v75
	v_lshlrev_b64 v[70:71], 13, v[70:71]
	global_store_dword v[122:123], v64, off offset:128
	v_or_b32_e32 v64, 24, v98
	v_lshl_add_u64 v[88:89], v[96:97], 0, v[70:71]
	v_add_u32_e32 v70, 42, v98
	v_ashrrev_i32_e32 v65, 31, v64
	v_ashrrev_i32_e32 v71, 31, v70
	v_lshlrev_b64 v[64:65], 13, v[64:65]
	v_lshlrev_b64 v[70:71], 13, v[70:71]
	v_lshl_add_u64 v[64:65], v[96:97], 0, v[64:65]
	v_lshl_add_u64 v[90:91], v[96:97], 0, v[70:71]
	v_add_u32_e32 v70, 43, v98
	global_load_dword v72, v[64:65], off
	v_ashrrev_i32_e32 v71, 31, v70
	v_lshlrev_b64 v[70:71], 13, v[70:71]
	v_lshl_add_u64 v[102:103], v[96:97], 0, v[70:71]
	v_add_u32_e32 v70, 48, v98
	v_ashrrev_i32_e32 v71, 31, v70
	v_lshlrev_b64 v[70:71], 13, v[70:71]
	global_load_dword v99, v[80:81], off
	global_load_dword v120, v[80:81], off offset:128
	global_load_dword v121, v[82:83], off
	global_load_dword v122, v[82:83], off offset:128
	global_load_dword v123, v[84:85], off
	global_load_dword v165, v[84:85], off offset:128
	v_lshl_add_u64 v[104:105], v[96:97], 0, v[70:71]
	v_add_u32_e32 v70, 49, v98
	v_ashrrev_i32_e32 v71, 31, v70
	v_lshlrev_b64 v[70:71], 13, v[70:71]
	v_lshl_add_u64 v[106:107], v[96:97], 0, v[70:71]
	v_add_u32_e32 v70, 50, v98
	v_ashrrev_i32_e32 v71, 31, v70
	v_lshlrev_b64 v[70:71], 13, v[70:71]
	v_lshl_add_u64 v[108:109], v[96:97], 0, v[70:71]
	v_add_u32_e32 v70, 51, v98
	v_ashrrev_i32_e32 v71, 31, v70
	global_load_dword v166, v[86:87], off
	global_load_dword v167, v[86:87], off offset:128
	global_load_dword v168, v[88:89], off
	global_load_dword v169, v[88:89], off offset:128
	global_load_dword v170, v[90:91], off
	global_load_dword v171, v[90:91], off offset:128
	global_load_dword v172, v[102:103], off
	global_load_dword v173, v[102:103], off offset:128
	v_lshlrev_b64 v[70:71], 13, v[70:71]
	v_lshl_add_u64 v[110:111], v[96:97], 0, v[70:71]
	v_add_u32_e32 v70, 56, v98
	v_ashrrev_i32_e32 v71, 31, v70
	v_lshlrev_b64 v[70:71], 13, v[70:71]
	v_lshl_add_u64 v[112:113], v[96:97], 0, v[70:71]
	v_add_u32_e32 v70, 57, v98
	v_ashrrev_i32_e32 v71, 31, v70
	v_lshlrev_b64 v[70:71], 13, v[70:71]
	v_lshl_add_u64 v[114:115], v[96:97], 0, v[70:71]
	v_add_u32_e32 v70, 58, v98
	global_load_dword v174, v[104:105], off
	global_load_dword v175, v[104:105], off offset:128
	global_load_dword v176, v[106:107], off
	global_load_dword v177, v[106:107], off offset:128
	global_load_dword v178, v[108:109], off
	global_load_dword v179, v[108:109], off offset:128
	global_load_dword v180, v[110:111], off
	global_load_dword v181, v[110:111], off offset:128
	v_ashrrev_i32_e32 v71, 31, v70
	v_lshlrev_b64 v[70:71], 13, v[70:71]
	global_load_dword v182, v[112:113], off
	global_load_dword v183, v[112:113], off offset:128
	v_lshl_add_u64 v[116:117], v[96:97], 0, v[70:71]
	v_add_u32_e32 v70, 59, v98
	v_ashrrev_i32_e32 v71, 31, v70
	v_lshlrev_b64 v[70:71], 13, v[70:71]
	v_lshl_add_u64 v[118:119], v[96:97], 0, v[70:71]
	global_load_dword v184, v[114:115], off
	global_load_dword v185, v[114:115], off offset:128
	global_load_dword v186, v[116:117], off
	global_load_dword v187, v[116:117], off offset:128
	global_load_dword v188, v[118:119], off
	global_load_dword v189, v[118:119], off offset:128
	v_or_b32_e32 v68, 26, v98
	v_or_b32_e32 v70, 27, v98
	v_ashrrev_i32_e32 v69, 31, v68
	v_ashrrev_i32_e32 v71, 31, v70
	v_lshlrev_b64 v[68:69], 13, v[68:69]
	v_lshlrev_b64 v[70:71], 13, v[70:71]
	v_add_co_u32_e32 v74, vcc, s15, v100
	v_lshl_add_u64 v[68:69], v[96:97], 0, v[68:69]
	v_lshl_add_u64 v[70:71], v[96:97], 0, v[70:71]
	global_load_dword v190, v[64:65], off offset:128
	global_load_dword v191, v[66:67], off
	global_load_dword v192, v[66:67], off offset:128
	global_load_dword v193, v[68:69], off
	global_load_dword v194, v[68:69], off offset:128
	global_load_dword v195, v[70:71], off
	global_load_dword v196, v[70:71], off offset:128
	v_addc_co_u32_e32 v75, vcc, 0, v101, vcc
	s_waitcnt vmcnt(37)
;     template <int MT> __device__ __forceinline__ void run(const Params& P, f32x16 (&acc)[MT][2], int rbase, int pn, int wc, int lane) const {
;     ...
;         for (int mt = 0; mt < MT; ++mt)
; #pragma unroll
;             for (int rg = 0; rg < 16; ++rg) { const int r = ROWOF(rb, mt, rg);
;                 float* y = P.out + O_Y + (size_t)r * 2048 + c0;
;                 y[0] = ALPHA * y[0] + acc[mt][0][rg]; y[32] = ALPHA * y[32] + acc[mt][1][rg]; }
	v_fmamk_f32 v72, v72, 0x3f9837f0, v92
	global_store_dword v[64:65], v72, off
	v_lshl_add_u64 v[72:73], v[100:101], 0, s[6:7]
	s_waitcnt vmcnt(36)
	v_fmamk_f32 v33, v120, 0x3f9837f0, v33
	global_load_dword v92, v[74:75], off
	global_load_dword v197, v[72:73], off offset:128
	v_fmamk_f32 v49, v99, 0x3f9837f0, v49
	global_store_dword v[80:81], v33, off offset:128
	s_waitcnt vmcnt(38)
	v_fmamk_f32 v33, v121, 0x3f9837f0, v50
	global_store_dword v[82:83], v33, off
	s_waitcnt vmcnt(38)
	v_fmamk_f32 v33, v122, 0x3f9837f0, v34
	global_store_dword v[82:83], v33, off offset:128
	s_waitcnt vmcnt(38)
	v_fmamk_f32 v33, v123, 0x3f9837f0, v51
	global_store_dword v[84:85], v33, off
	s_waitcnt vmcnt(38)
	v_fmamk_f32 v33, v165, 0x3f9837f0, v35
	global_store_dword v[84:85], v33, off offset:128
	s_waitcnt vmcnt(38)
	v_fmamk_f32 v33, v166, 0x3f9837f0, v52
	global_store_dword v[86:87], v33, off
	s_waitcnt vmcnt(38)
	v_fmamk_f32 v33, v167, 0x3f9837f0, v36
	global_store_dword v[86:87], v33, off offset:128
	s_waitcnt vmcnt(38)
	v_fmamk_f32 v33, v168, 0x3f9837f0, v53
	global_store_dword v[88:89], v33, off
	s_waitcnt vmcnt(38)
	v_fmamk_f32 v33, v169, 0x3f9837f0, v37
	global_store_dword v[88:89], v33, off offset:128
	s_waitcnt vmcnt(38)
	v_fmamk_f32 v33, v170, 0x3f9837f0, v54
	global_store_dword v[90:91], v33, off
	s_waitcnt vmcnt(38)
	v_fmamk_f32 v33, v171, 0x3f9837f0, v38
	global_store_dword v[90:91], v33, off offset:128
	s_waitcnt vmcnt(38)
	v_fmamk_f32 v33, v172, 0x3f9837f0, v55
	global_store_dword v[102:103], v33, off
	s_waitcnt vmcnt(38)
	v_fmamk_f32 v33, v173, 0x3f9837f0, v39
	global_store_dword v[102:103], v33, off offset:128
	s_waitcnt vmcnt(38)
	v_fmamk_f32 v33, v174, 0x3f9837f0, v56
	global_store_dword v[104:105], v33, off
	s_waitcnt vmcnt(38)
	v_fmamk_f32 v33, v175, 0x3f9837f0, v40
	global_store_dword v[104:105], v33, off offset:128
	s_waitcnt vmcnt(38)
	v_fmamk_f32 v33, v176, 0x3f9837f0, v57
	global_store_dword v[106:107], v33, off
	s_waitcnt vmcnt(38)
	v_fmamk_f32 v33, v177, 0x3f9837f0, v41
	global_store_dword v[106:107], v33, off offset:128
	s_waitcnt vmcnt(38)
	v_fmamk_f32 v33, v178, 0x3f9837f0, v58
	global_store_dword v[108:109], v33, off
	s_waitcnt vmcnt(38)
	v_fmamk_f32 v33, v179, 0x3f9837f0, v42
	global_store_dword v[108:109], v33, off offset:128
	s_waitcnt vmcnt(38)
	v_fmamk_f32 v33, v180, 0x3f9837f0, v59
	global_store_dword v[110:111], v33, off
	s_waitcnt vmcnt(38)
	v_fmamk_f32 v33, v181, 0x3f9837f0, v43
	global_store_dword v[110:111], v33, off offset:128
	s_waitcnt vmcnt(38)
	v_fmamk_f32 v33, v182, 0x3f9837f0, v60
	global_store_dword v[112:113], v33, off
	s_waitcnt vmcnt(38)
	v_fmamk_f32 v33, v183, 0x3f9837f0, v44
	global_store_dword v[112:113], v33, off offset:128
	s_waitcnt vmcnt(38)
	v_fmamk_f32 v33, v184, 0x3f9837f0, v61
	global_store_dword v[114:115], v33, off
	s_waitcnt vmcnt(38)
	v_fmamk_f32 v33, v185, 0x3f9837f0, v45
	global_store_dword v[114:115], v33, off offset:128
	s_waitcnt vmcnt(38)
	v_fmamk_f32 v33, v186, 0x3f9837f0, v62
	v_add_u32_e32 v38, 0x41, v98
	v_add_u32_e32 v40, 0x42, v98
	v_add_u32_e32 v42, 0x43, v98
	global_store_dword v[116:117], v33, off
	s_waitcnt vmcnt(38)
	v_fmamk_f32 v33, v187, 0x3f9837f0, v46
	s_waitcnt vmcnt(37)
	v_fmac_f32_e32 v63, 0x3f9837f0, v188
	s_waitcnt vmcnt(36)
	v_fmac_f32_e32 v47, 0x3f9837f0, v189
	v_add_co_u32_e32 v36, vcc, s16, v100
	v_ashrrev_i32_e32 v39, 31, v38
	v_ashrrev_i32_e32 v41, 31, v40
	v_ashrrev_i32_e32 v43, 31, v42
	global_store_dword v[80:81], v49, off
	global_store_dword v[116:117], v33, off offset:128
	global_store_dword v[118:119], v63, off
	global_store_dword v[118:119], v47, off offset:128
	v_addc_co_u32_e32 v37, vcc, 0, v101, vcc
	v_lshlrev_b64 v[38:39], 13, v[38:39]
	v_lshlrev_b64 v[40:41], 13, v[40:41]
	v_lshlrev_b64 v[42:43], 13, v[42:43]
	v_lshl_add_u64 v[34:35], v[100:101], 0, s[8:9]
	v_lshl_add_u64 v[38:39], v[96:97], 0, v[38:39]
	v_lshl_add_u64 v[40:41], v[96:97], 0, v[40:41]
	v_lshl_add_u64 v[42:43], v[96:97], 0, v[42:43]
	global_load_dword v33, v[36:37], off
	global_load_dword v49, v[38:39], off
	global_load_dword v86, v[38:39], off offset:128
	global_load_dword v87, v[40:41], off
	global_load_dword v88, v[40:41], off offset:128
	global_load_dword v89, v[42:43], off
	global_load_dword v90, v[42:43], off offset:128
	global_load_dword v91, v[34:35], off offset:128
	v_add_u32_e32 v44, 0x48, v98
	v_ashrrev_i32_e32 v45, 31, v44
	v_add_u32_e32 v46, 0x49, v98
	v_add_u32_e32 v50, 0x4a, v98
	v_add_u32_e32 v52, 0x4b, v98
	v_lshlrev_b64 v[44:45], 13, v[44:45]
	v_ashrrev_i32_e32 v47, 31, v46
	v_ashrrev_i32_e32 v51, 31, v50
	v_ashrrev_i32_e32 v53, 31, v52
	v_lshl_add_u64 v[44:45], v[96:97], 0, v[44:45]
	v_lshlrev_b64 v[46:47], 13, v[46:47]
	v_lshlrev_b64 v[50:51], 13, v[50:51]
	v_lshlrev_b64 v[52:53], 13, v[52:53]
	v_lshl_add_u64 v[46:47], v[96:97], 0, v[46:47]
	v_lshl_add_u64 v[50:51], v[96:97], 0, v[50:51]
	v_lshl_add_u64 v[52:53], v[96:97], 0, v[52:53]
	global_load_dword v99, v[44:45], off
	global_load_dword v100, v[44:45], off offset:128
	global_load_dword v101, v[46:47], off
	global_load_dword v102, v[46:47], off offset:128
	global_load_dword v103, v[50:51], off
	global_load_dword v104, v[50:51], off offset:128
	global_load_dword v105, v[52:53], off
	global_load_dword v106, v[52:53], off offset:128
	v_add_u32_e32 v54, 0x50, v98
	v_ashrrev_i32_e32 v55, 31, v54
	v_add_u32_e32 v56, 0x51, v98
	v_add_u32_e32 v58, 0x52, v98
	v_add_u32_e32 v60, 0x53, v98
	v_lshlrev_b64 v[54:55], 13, v[54:55]
	v_ashrrev_i32_e32 v57, 31, v56
	v_ashrrev_i32_e32 v59, 31, v58
	v_ashrrev_i32_e32 v61, 31, v60
	v_add_u32_e32 v62, 0x58, v98
;     template <int MT> __device__ __forceinline__ void run(const Params& P, f32x16 (&acc)[MT][2], int rbase, int pn, int wc, int lane) const {
;     ...
;         for (int mt = 0; mt < MT; ++mt)
; #pragma unroll
;             for (int rg = 0; rg < 16; ++rg) { const int r = ROWOF(rb, mt, rg);
;                 float* y = P.out + O_Y + (size_t)r * 2048 + c0;
;                 y[0] = ALPHA * y[0] + acc[mt][0][rg]; y[32] = ALPHA * y[32] + acc[mt][1][rg]; }
	v_lshl_add_u64 v[54:55], v[96:97], 0, v[54:55]
	v_lshlrev_b64 v[56:57], 13, v[56:57]
	v_lshlrev_b64 v[58:59], 13, v[58:59]
	v_lshlrev_b64 v[60:61], 13, v[60:61]
	v_ashrrev_i32_e32 v63, 31, v62
	v_lshl_add_u64 v[56:57], v[96:97], 0, v[56:57]
	v_lshl_add_u64 v[58:59], v[96:97], 0, v[58:59]
	v_lshl_add_u64 v[60:61], v[96:97], 0, v[60:61]
	global_load_dword v107, v[54:55], off
	global_load_dword v108, v[54:55], off offset:128
	global_load_dword v109, v[56:57], off
	global_load_dword v110, v[56:57], off offset:128
	global_load_dword v111, v[58:59], off
	global_load_dword v112, v[58:59], off offset:128
	global_load_dword v113, v[60:61], off
	global_load_dword v114, v[60:61], off offset:128
	v_lshlrev_b64 v[62:63], 13, v[62:63]
	v_lshl_add_u64 v[62:63], v[96:97], 0, v[62:63]
	global_load_dword v115, v[62:63], off
	global_load_dword v116, v[62:63], off offset:128
	v_add_u32_e32 v80, 0x59, v98
	v_add_u32_e32 v84, 0x5b, v98
	v_ashrrev_i32_e32 v81, 31, v80
	v_add_u32_e32 v82, 0x5a, v98
	v_ashrrev_i32_e32 v85, 31, v84
	v_lshlrev_b64 v[80:81], 13, v[80:81]
	v_ashrrev_i32_e32 v83, 31, v82
	v_lshlrev_b64 v[84:85], 13, v[84:85]
	v_lshl_add_u64 v[80:81], v[96:97], 0, v[80:81]
	v_lshlrev_b64 v[82:83], 13, v[82:83]
	v_lshl_add_u64 v[84:85], v[96:97], 0, v[84:85]
	v_lshl_add_u64 v[82:83], v[96:97], 0, v[82:83]
	global_load_dword v117, v[80:81], off
	global_load_dword v118, v[80:81], off offset:128
	global_load_dword v119, v[82:83], off
	global_load_dword v120, v[82:83], off offset:128
	global_load_dword v96, v[84:85], off
	global_load_dword v97, v[84:85], off offset:128
	s_waitcnt vmcnt(62)
	v_fmamk_f32 v76, v190, 0x3f9837f0, v76
	global_store_dword v[64:65], v76, off offset:128
	v_fmamk_f32 v64, v191, 0x3f9837f0, v93
	global_store_dword v[66:67], v64, off
	v_fmamk_f32 v64, v192, 0x3f9837f0, v77
	global_store_dword v[66:67], v64, off offset:128
	v_fmamk_f32 v64, v193, 0x3f9837f0, v94
	global_store_dword v[68:69], v64, off
	v_fmamk_f32 v64, v194, 0x3f9837f0, v78
	v_fmac_f32_e32 v95, 0x3f9837f0, v195
	v_fmac_f32_e32 v79, 0x3f9837f0, v196
	v_fmamk_f32 v48, v92, 0x3f9837f0, v48
	v_fmamk_f32 v32, v197, 0x3f9837f0, v32
	global_store_dword v[68:69], v64, off offset:128
	global_store_dword v[70:71], v95, off
	global_store_dword v[70:71], v79, off offset:128
	global_store_dword v[74:75], v48, off
	global_store_dword v[72:73], v32, off offset:128
	s_waitcnt vmcnt(40)
	v_fmamk_f32 v16, v33, 0x3f9837f0, v16
	global_store_dword v[36:37], v16, off
	s_waitcnt vmcnt(34)
	v_fmamk_f32 v0, v91, 0x3f9837f0, v0
	global_store_dword v[34:35], v0, off offset:128
	v_fmamk_f32 v0, v49, 0x3f9837f0, v17
	global_store_dword v[38:39], v0, off
	v_fmamk_f32 v0, v86, 0x3f9837f0, v1
	global_store_dword v[38:39], v0, off offset:128
	v_fmamk_f32 v0, v87, 0x3f9837f0, v18
	global_store_dword v[40:41], v0, off
	v_fmamk_f32 v0, v88, 0x3f9837f0, v2
	global_store_dword v[40:41], v0, off offset:128
	v_fmamk_f32 v0, v89, 0x3f9837f0, v19
	global_store_dword v[42:43], v0, off
	v_fmamk_f32 v0, v90, 0x3f9837f0, v3
	global_store_dword v[42:43], v0, off offset:128
	s_waitcnt vmcnt(40)
	v_fmamk_f32 v0, v99, 0x3f9837f0, v20
	global_store_dword v[44:45], v0, off
	s_waitcnt vmcnt(40)
	v_fmamk_f32 v0, v100, 0x3f9837f0, v4
	global_store_dword v[44:45], v0, off offset:128
	s_waitcnt vmcnt(40)
	v_fmamk_f32 v0, v101, 0x3f9837f0, v21
	global_store_dword v[46:47], v0, off
	s_waitcnt vmcnt(40)
	v_fmamk_f32 v0, v102, 0x3f9837f0, v5
	global_store_dword v[46:47], v0, off offset:128
	s_waitcnt vmcnt(40)
	v_fmamk_f32 v0, v103, 0x3f9837f0, v22
	global_store_dword v[50:51], v0, off
	s_waitcnt vmcnt(40)
	v_fmamk_f32 v0, v104, 0x3f9837f0, v6
	global_store_dword v[50:51], v0, off offset:128
	s_waitcnt vmcnt(40)
	v_fmamk_f32 v0, v105, 0x3f9837f0, v23
	global_store_dword v[52:53], v0, off
	s_waitcnt vmcnt(40)
	v_fmamk_f32 v0, v106, 0x3f9837f0, v7
	global_store_dword v[52:53], v0, off offset:128
	s_waitcnt vmcnt(40)
	v_fmamk_f32 v0, v107, 0x3f9837f0, v24
	global_store_dword v[54:55], v0, off
	s_waitcnt vmcnt(40)
	v_fmamk_f32 v0, v108, 0x3f9837f0, v8
	global_store_dword v[54:55], v0, off offset:128
	s_waitcnt vmcnt(40)
	v_fmamk_f32 v0, v109, 0x3f9837f0, v25
	global_store_dword v[56:57], v0, off
	s_waitcnt vmcnt(40)
	v_fmamk_f32 v0, v110, 0x3f9837f0, v9
	global_store_dword v[56:57], v0, off offset:128
	s_waitcnt vmcnt(40)
	v_fmamk_f32 v0, v111, 0x3f9837f0, v26
	global_store_dword v[58:59], v0, off
	s_waitcnt vmcnt(40)
	v_fmamk_f32 v0, v112, 0x3f9837f0, v10
	global_store_dword v[58:59], v0, off offset:128
	s_waitcnt vmcnt(40)
	v_fmamk_f32 v0, v113, 0x3f9837f0, v27
	global_store_dword v[60:61], v0, off
	s_waitcnt vmcnt(40)
	v_fmamk_f32 v0, v114, 0x3f9837f0, v11
	global_store_dword v[60:61], v0, off offset:128
	s_waitcnt vmcnt(40)
	v_fmamk_f32 v0, v115, 0x3f9837f0, v28
	global_store_dword v[62:63], v0, off
	s_waitcnt vmcnt(40)
	v_fmamk_f32 v0, v116, 0x3f9837f0, v12
	global_store_dword v[62:63], v0, off offset:128
	s_waitcnt vmcnt(40)
	v_fmamk_f32 v0, v117, 0x3f9837f0, v29
	global_store_dword v[80:81], v0, off
	s_waitcnt vmcnt(40)
	v_fmamk_f32 v0, v118, 0x3f9837f0, v13
	global_store_dword v[80:81], v0, off offset:128
	s_waitcnt vmcnt(40)
	v_fmamk_f32 v0, v119, 0x3f9837f0, v30
	global_store_dword v[82:83], v0, off
	s_waitcnt vmcnt(40)
	v_fmamk_f32 v0, v120, 0x3f9837f0, v14
	s_waitcnt vmcnt(39)
	v_fmac_f32_e32 v31, 0x3f9837f0, v96
	s_waitcnt vmcnt(38)
	v_fmac_f32_e32 v15, 0x3f9837f0, v97
	global_store_dword v[82:83], v0, off offset:128
	global_store_dword v[84:85], v31, off
	global_store_dword v[84:85], v15, off offset:128
	s_branch .LBB0_2778

; __global__ void __launch_bounds__(NTHREADS) fwd_megakernel(Params P) {
;     extern __shared__ __attribute__((aligned(16))) char lds[];
	.amdhsa_kernel _Z14fwd_megakernel6Params
		.amdhsa_group_segment_fixed_size 16
		.amdhsa_private_segment_fixed_size 0
		.amdhsa_kernarg_size 432
		.amdhsa_user_sgpr_count 2
		.amdhsa_user_sgpr_dispatch_ptr 0
		.amdhsa_user_sgpr_queue_ptr 0
		.amdhsa_user_sgpr_kernarg_segment_ptr 1
		.amdhsa_user_sgpr_dispatch_id 0
		.amdhsa_user_sgpr_kernarg_preload_length 0
		.amdhsa_user_sgpr_kernarg_preload_offset 0
		.amdhsa_user_sgpr_private_segment_size 0
		.amdhsa_uses_dynamic_stack 0
		.amdhsa_enable_private_segment 0
		.amdhsa_system_sgpr_workgroup_id_x 1
		.amdhsa_system_sgpr_workgroup_id_y 0
		.amdhsa_system_sgpr_workgroup_id_z 0
		.amdhsa_system_sgpr_workgroup_info 0
		.amdhsa_system_vgpr_workitem_id 2
		.amdhsa_next_free_vgpr 253
		.amdhsa_next_free_sgpr 100
		.amdhsa_accum_offset 256
		.amdhsa_reserve_vcc 1
		.amdhsa_float_round_mode_32 0
		.amdhsa_float_round_mode_16_64 0
		.amdhsa_float_denorm_mode_32 3
		.amdhsa_float_denorm_mode_16_64 3
		.amdhsa_dx10_clamp 1
		.amdhsa_ieee_mode 1
		.amdhsa_fp16_overflow 0
		.amdhsa_tg_split 0
		.amdhsa_exception_fp_ieee_invalid_op 0
		.amdhsa_exception_fp_denorm_src 0
		.amdhsa_exception_fp_ieee_div_zero 0
		.amdhsa_exception_fp_ieee_overflow 0
		.amdhsa_exception_fp_ieee_underflow 0
		.amdhsa_exception_fp_ieee_inexact 0
		.amdhsa_exception_int_div_zero 0
	.end_amdhsa_kernel

; __global__ void __launch_bounds__(NTHREADS) fwd_megakernel(Params P) {
amdhsa.kernels:
  - .agpr_count:     0
    .args:
      - .offset:         0
        .size:           176
        .value_kind:     by_value
      - .offset:         176
        .size:           4
        .value_kind:     hidden_block_count_x
      - .offset:         180
        .size:           4
        .value_kind:     hidden_block_count_y
      - .offset:         184
        .size:           4
        .value_kind:     hidden_block_count_z
      - .offset:         188
        .size:           2
        .value_kind:     hidden_group_size_x
      - .offset:         190
        .size:           2
        .value_kind:     hidden_group_size_y
      - .offset:         192
        .size:           2
        .value_kind:     hidden_group_size_z
      - .offset:         194
        .size:           2
        .value_kind:     hidden_remainder_x
      - .offset:         196
        .size:           2
        .value_kind:     hidden_remainder_y
      - .offset:         198
        .size:           2
        .value_kind:     hidden_remainder_z
      - .offset:         216
        .size:           8
        .value_kind:     hidden_global_offset_x
      - .offset:         224
        .size:           8
        .value_kind:     hidden_global_offset_y
      - .offset:         232
        .size:           8
        .value_kind:     hidden_global_offset_z
      - .offset:         240
        .size:           2
        .value_kind:     hidden_grid_dims
      - .offset:         264
        .size:           8
        .value_kind:     hidden_multigrid_sync_arg
      - .offset:         296
        .size:           4
        .value_kind:     hidden_dynamic_lds_size
    .group_segment_fixed_size: 16
    .kernarg_segment_align: 8
    .kernarg_segment_size: 432
    .language:       OpenCL C
    .language_version:
      - 2
      - 0
    .max_flat_workgroup_size: 512
    .name:           _Z14fwd_megakernel6Params
    .private_segment_fixed_size: 0
    .sgpr_count:     106
    .sgpr_spill_count: 52
    .symbol:         _Z14fwd_megakernel6Params.kd
    .uniform_work_group_size: 1
    .uses_dynamic_stack: false
    .vgpr_count:     253
    .vgpr_spill_count: 0
    .wavefront_size: 64
